# P7 epilogue: rstd scaling of all accumulator groups hoisted into the conv-tap load latency window (before the first vmcnt wait)
# speedup vs baseline: 1.0110x; 1.0110x over previous
; #define PG8_LAS __attribute__((address_space(3)))
; __device__ __forceinline__ unsigned cvt_pk_bf16(float lo, float hi) { unsigned r; asm volatile("v_cvt_pk_bf16_f32 %0, %1, %2" : "=v"(r) : "v"(lo), "v"(hi)); return r; }
; __device__ __forceinline__ float dpp_ror1(float x) { return __int_as_float(__builtin_amdgcn_update_dpp(0, __float_as_int(x), 0x121, 0xf, 0xf, false)); }
; __device__ __forceinline__ float dpp_ror2(float x) { return __int_as_float(__builtin_amdgcn_update_dpp(0, __float_as_int(x), 0x122, 0xf, 0xf, false)); }
;     __device__ __forceinline__ void operator()(const f32x4 (&acc)[2][2][4][2], const Unit& u, int wr, int wc, int fr, int fq) const {
;     ...
;                     for (int n = 0; n < 2; ++n) { const f32x4 x = acc[ai][bj][3][n] * rs[ai][3];
;                         *(PG8_LAS f32x4*)(halo + ((ai * 2 + wr) * 2 + (fr - 14)) * 256 + bj * HALF + lcol + 4 * n) = x;
;                         if (ai == 1 && wr == 1) *(f32x4*)(rawh + (size_t)(u.pm * 2 + (fr - 14)) * FF2 + bj * FF + gcol + 4 * n) = x; }
;     ...
;                 for (int m = 0; m < 4; ++m) {
;                     f32x4 cur[2], h[2];
; #pragma unroll
;                     for (int bj = 0; bj < 2; ++bj) { cur[bj] = acc[ai][bj][m][n] * rs[ai][m]; f32x4 x1, x2;
; #pragma unroll
;                         for (int e = 0; e < 4; ++e) { const float c1 = dpp_ror1(cur[bj][e]), p1 = dpp_ror1(pg[bj][e]), c2 = dpp_ror2(cur[bj][e]), p2 = dpp_ror2(pg[bj][e]);
;                             x1[e] = fr >= 1 ? c1 : p1; x2[e] = fr >= 2 ? c2 : p2; }
;                         h[bj] = bb[bj] + w0[bj] * x2 + w1[bj] * x1 + w2[bj] * cur[bj]; }
;                     if (ai == 0 && wr == 0 && m == 0 && fr < 2) {
;                         *(f32x4*)(hc0 + (size_t)(u.pm * 2 + fr) * FF2 + gcol + 4 * n) = h[0]; *(f32x4*)(hc0 + (size_t)(u.pm * 2 + fr) * FF2 + FF + gcol + 4 * n) = h[1]; }
;                     f32x4 a;
; #pragma unroll
;                     for (int e = 0; e < 4; ++e) { const float g = h[0][e]; a[e] = g * __builtin_amdgcn_rcpf(1.0f + __builtin_amdgcn_exp2f(-1.4426950408889634f * g)) * h[1][e]; }
;                     const unsigned p0 = cvt_pk_bf16(a[0], a[1]), p1 = cvt_pk_bf16(a[2], a[3]);
;                     if (n == 0) { pk_lo[ai][m][0] = p0; pk_lo[ai][m][1] = p1; }
.Lp7_hr0:
	ds_read_b128 v[178:181], v214
	ds_read_b128 v[182:185], v214 offset:512
	v_pk_mul_f32 v[124:125], v[124:125], v[228:229] op_sel_hi:[1,0]
	v_pk_mul_f32 v[126:127], v[126:127], v[228:229] op_sel_hi:[1,0]
	v_pk_mul_f32 v[120:121], v[120:121], v[228:229] op_sel_hi:[1,0]
	v_pk_mul_f32 v[122:123], v[122:123], v[228:229] op_sel_hi:[1,0]
	v_pk_mul_f32 v[116:117], v[116:117], v[230:231] op_sel_hi:[1,0]
	v_pk_mul_f32 v[118:119], v[118:119], v[230:231] op_sel_hi:[1,0]
	v_pk_mul_f32 v[112:113], v[112:113], v[230:231] op_sel_hi:[1,0]
	v_pk_mul_f32 v[114:115], v[114:115], v[230:231] op_sel_hi:[1,0]
	v_pk_mul_f32 v[108:109], v[108:109], v[232:233] op_sel_hi:[1,0]
	v_pk_mul_f32 v[110:111], v[110:111], v[232:233] op_sel_hi:[1,0]
	v_pk_mul_f32 v[104:105], v[104:105], v[232:233] op_sel_hi:[1,0]
	v_pk_mul_f32 v[106:107], v[106:107], v[232:233] op_sel_hi:[1,0]
	v_pk_mul_f32 v[92:93], v[92:93], v[236:237] op_sel_hi:[1,0]
	v_pk_mul_f32 v[94:95], v[94:95], v[236:237] op_sel_hi:[1,0]
	v_pk_mul_f32 v[88:89], v[88:89], v[236:237] op_sel_hi:[1,0]
	v_pk_mul_f32 v[90:91], v[90:91], v[236:237] op_sel_hi:[1,0]
	v_pk_mul_f32 v[84:85], v[84:85], v[238:239] op_sel_hi:[1,0]
	v_pk_mul_f32 v[86:87], v[86:87], v[238:239] op_sel_hi:[1,0]
	v_pk_mul_f32 v[80:81], v[80:81], v[238:239] op_sel_hi:[1,0]
	v_pk_mul_f32 v[82:83], v[82:83], v[238:239] op_sel_hi:[1,0]
	v_pk_mul_f32 v[76:77], v[76:77], v[240:241] op_sel_hi:[1,0]
	v_pk_mul_f32 v[78:79], v[78:79], v[240:241] op_sel_hi:[1,0]
	v_pk_mul_f32 v[72:73], v[72:73], v[240:241] op_sel_hi:[1,0]
	v_pk_mul_f32 v[74:75], v[74:75], v[240:241] op_sel_hi:[1,0]
	v_pk_mul_f32 v[60:61], v[60:61], v[228:229] op_sel_hi:[1,0]
	v_pk_mul_f32 v[62:63], v[62:63], v[228:229] op_sel_hi:[1,0]
	v_pk_mul_f32 v[56:57], v[56:57], v[228:229] op_sel_hi:[1,0]
	v_pk_mul_f32 v[58:59], v[58:59], v[228:229] op_sel_hi:[1,0]
	v_pk_mul_f32 v[52:53], v[52:53], v[230:231] op_sel_hi:[1,0]
	v_pk_mul_f32 v[54:55], v[54:55], v[230:231] op_sel_hi:[1,0]
	v_pk_mul_f32 v[48:49], v[48:49], v[230:231] op_sel_hi:[1,0]
	v_pk_mul_f32 v[50:51], v[50:51], v[230:231] op_sel_hi:[1,0]
	v_pk_mul_f32 v[44:45], v[44:45], v[232:233] op_sel_hi:[1,0]
	v_pk_mul_f32 v[46:47], v[46:47], v[232:233] op_sel_hi:[1,0]
	v_pk_mul_f32 v[40:41], v[40:41], v[232:233] op_sel_hi:[1,0]
	v_pk_mul_f32 v[42:43], v[42:43], v[232:233] op_sel_hi:[1,0]
	v_pk_mul_f32 v[28:29], v[28:29], v[236:237] op_sel_hi:[1,0]
	v_pk_mul_f32 v[30:31], v[30:31], v[236:237] op_sel_hi:[1,0]
	v_pk_mul_f32 v[24:25], v[24:25], v[236:237] op_sel_hi:[1,0]
	v_pk_mul_f32 v[26:27], v[26:27], v[236:237] op_sel_hi:[1,0]
	v_pk_mul_f32 v[20:21], v[20:21], v[238:239] op_sel_hi:[1,0]
	v_pk_mul_f32 v[22:23], v[22:23], v[238:239] op_sel_hi:[1,0]
	v_pk_mul_f32 v[16:17], v[16:17], v[238:239] op_sel_hi:[1,0]
	v_pk_mul_f32 v[18:19], v[18:19], v[238:239] op_sel_hi:[1,0]
	v_pk_mul_f32 v[12:13], v[12:13], v[240:241] op_sel_hi:[1,0]
	v_pk_mul_f32 v[14:15], v[14:15], v[240:241] op_sel_hi:[1,0]
	v_pk_mul_f32 v[8:9], v[8:9], v[240:241] op_sel_hi:[1,0]
	v_pk_mul_f32 v[10:11], v[10:11], v[240:241] op_sel_hi:[1,0]
	s_waitcnt vmcnt(0) lgkmcnt(0)
	v_pk_fma_f32 v[220:221], v[136:137], v[124:125], v[140:141]
	v_pk_fma_f32 v[222:223], v[138:139], v[126:127], v[142:143]
	v_pk_fma_f32 v[224:225], v[152:153], v[120:121], v[156:157]
	v_pk_fma_f32 v[226:227], v[154:155], v[122:123], v[158:159]
	v_cndmask_b32_e64 v188, v124, v160, s[98:99]
	v_cndmask_b32_e64 v189, v125, v161, s[98:99]
	v_cndmask_b32_e64 v196, v126, v162, s[98:99]
	v_cndmask_b32_e64 v197, v127, v163, s[98:99]
	v_cndmask_b32_e64 v200, v120, v164, s[98:99]
	v_cndmask_b32_e64 v201, v121, v165, s[98:99]
	v_cndmask_b32_e64 v204, v122, v166, s[98:99]
	v_cndmask_b32_e64 v205, v123, v167, s[98:99]
	v_fmac_f32_dpp v220, v188, v132 row_ror:1 row_mask:0xf bank_mask:0xf
	v_fmac_f32_dpp v221, v189, v133 row_ror:1 row_mask:0xf bank_mask:0xf
	v_fmac_f32_dpp v222, v196, v134 row_ror:1 row_mask:0xf bank_mask:0xf
	v_fmac_f32_dpp v223, v197, v135 row_ror:1 row_mask:0xf bank_mask:0xf
	v_fmac_f32_dpp v224, v200, v148 row_ror:1 row_mask:0xf bank_mask:0xf
	v_fmac_f32_dpp v225, v201, v149 row_ror:1 row_mask:0xf bank_mask:0xf
	v_fmac_f32_dpp v226, v204, v150 row_ror:1 row_mask:0xf bank_mask:0xf
	v_fmac_f32_dpp v227, v205, v151 row_ror:1 row_mask:0xf bank_mask:0xf
	v_cndmask_b32_e64 v188, v160, v124, s[40:41]
	v_cndmask_b32_e64 v189, v161, v125, s[40:41]
	v_cndmask_b32_e64 v196, v162, v126, s[40:41]
	v_cndmask_b32_e64 v197, v163, v127, s[40:41]
	v_cndmask_b32_e64 v200, v164, v120, s[40:41]
	v_cndmask_b32_e64 v201, v165, v121, s[40:41]
	v_cndmask_b32_e64 v204, v166, v122, s[40:41]
	v_cndmask_b32_e64 v205, v167, v123, s[40:41]
	v_fmac_f32_dpp v220, v188, v128 row_ror:2 row_mask:0xf bank_mask:0xf
	v_fmac_f32_dpp v221, v189, v129 row_ror:2 row_mask:0xf bank_mask:0xf
	v_fmac_f32_dpp v222, v196, v130 row_ror:2 row_mask:0xf bank_mask:0xf
	v_fmac_f32_dpp v223, v197, v131 row_ror:2 row_mask:0xf bank_mask:0xf
	v_fmac_f32_dpp v224, v200, v144 row_ror:2 row_mask:0xf bank_mask:0xf
	v_fmac_f32_dpp v225, v201, v145 row_ror:2 row_mask:0xf bank_mask:0xf
	v_fmac_f32_dpp v226, v204, v146 row_ror:2 row_mask:0xf bank_mask:0xf
	v_fmac_f32_dpp v227, v205, v147 row_ror:2 row_mask:0xf bank_mask:0xf
	s_and_saveexec_b64 s[0:1], s[12:13]
	global_store_dwordx4 v241, v[220:223], s[84:85]
	global_store_dwordx4 v249, v[224:227], s[84:85]
	s_or_b64 exec, exec, s[0:1]
	v_pk_mul_f32 v[190:191], v[220:221], s[100:101] op_sel_hi:[1,0]
	v_pk_mul_f32 v[250:251], v[222:223], s[100:101] op_sel_hi:[1,0]
	v_exp_f32_e32 v190, v190
	v_exp_f32_e32 v191, v191
	v_exp_f32_e32 v250, v250
	v_exp_f32_e32 v251, v251
	v_pk_mul_f32 v[220:221], v[220:221], v[224:225]
	v_pk_mul_f32 v[222:223], v[222:223], v[226:227]
	v_pk_add_f32 v[190:191], v[190:191], 1.0 op_sel_hi:[1,0]
	v_pk_add_f32 v[250:251], v[250:251], 1.0 op_sel_hi:[1,0]
	v_rcp_f32_e32 v190, v190
	v_rcp_f32_e32 v191, v191
	v_rcp_f32_e32 v250, v250
	v_rcp_f32_e32 v251, v251
	v_pk_mul_f32 v[220:221], v[220:221], v[190:191]
	v_pk_mul_f32 v[222:223], v[222:223], v[250:251]
	v_cvt_pk_bf16_f32 v186, v220, v221
	v_cvt_pk_bf16_f32 v187, v222, v223
	s_and_b64 vcc, exec, s[20:21]
	s_cbranch_vccnz .Lp7_norawh
	s_mov_b64 s[0:1], exec
	s_andn2_b64 exec, exec, s[40:41]
	v_add_u32_e32 v229, s11, v210
	v_mad_u32_u24 v229, v229, s70, v233
	v_add_u32_e32 v231, 0x2c00, v229
	global_store_dwordx4 v229, v[68:71], s[18:19]
	global_store_dwordx4 v229, v[4:7], s[18:19] offset:16
	global_store_dwordx4 v231, v[64:67], s[18:19]
	global_store_dwordx4 v231, v[0:3], s[18:19] offset:16
	s_mov_b64 exec, s[0:1]
; __device__ __forceinline__ unsigned cvt_pk_bf16(float lo, float hi) { unsigned r; asm volatile("v_cvt_pk_bf16_f32 %0, %1, %2" : "=v"(r) : "v"(lo), "v"(hi)); return r; }
; __device__ __forceinline__ float dpp_ror1(float x) { return __int_as_float(__builtin_amdgcn_update_dpp(0, __float_as_int(x), 0x121, 0xf, 0xf, false)); }
; __device__ __forceinline__ float dpp_ror2(float x) { return __int_as_float(__builtin_amdgcn_update_dpp(0, __float_as_int(x), 0x122, 0xf, 0xf, false)); }
;     __device__ __forceinline__ void operator()(const f32x4 (&acc)[2][2][4][2], const Unit& u, int wr, int wc, int fr, int fq) const {
;     ...
;                 for (int m = 0; m < 4; ++m) {
;                     f32x4 cur[2], h[2];
; #pragma unroll
;                     for (int bj = 0; bj < 2; ++bj) { cur[bj] = acc[ai][bj][m][n] * rs[ai][m]; f32x4 x1, x2;
; #pragma unroll
;                         for (int e = 0; e < 4; ++e) { const float c1 = dpp_ror1(cur[bj][e]), p1 = dpp_ror1(pg[bj][e]), c2 = dpp_ror2(cur[bj][e]), p2 = dpp_ror2(pg[bj][e]);
;                             x1[e] = fr >= 1 ? c1 : p1; x2[e] = fr >= 2 ? c2 : p2; }
;                         h[bj] = bb[bj] + w0[bj] * x2 + w1[bj] * x1 + w2[bj] * cur[bj]; }
;                     if (ai == 0 && wr == 0 && m == 0 && fr < 2) {
;                         *(f32x4*)(hc0 + (size_t)(u.pm * 2 + fr) * FF2 + gcol + 4 * n) = h[0]; *(f32x4*)(hc0 + (size_t)(u.pm * 2 + fr) * FF2 + FF + gcol + 4 * n) = h[1]; }
;                     f32x4 a;
; #pragma unroll
;                     for (int e = 0; e < 4; ++e) { const float g = h[0][e]; a[e] = g * __builtin_amdgcn_rcpf(1.0f + __builtin_amdgcn_exp2f(-1.4426950408889634f * g)) * h[1][e]; }
;                     const unsigned p0 = cvt_pk_bf16(a[0], a[1]), p1 = cvt_pk_bf16(a[2], a[3]);
;                     if (n == 0) { pk_lo[ai][m][0] = p0; pk_lo[ai][m][1] = p1; }
.Lp7_norawh:
	v_pk_fma_f32 v[220:221], v[136:137], v[116:117], v[140:141]
	v_pk_fma_f32 v[222:223], v[138:139], v[118:119], v[142:143]
	v_pk_fma_f32 v[224:225], v[152:153], v[112:113], v[156:157]
	v_pk_fma_f32 v[226:227], v[154:155], v[114:115], v[158:159]
	v_cndmask_b32_e64 v188, v116, v124, s[98:99]
	v_cndmask_b32_e64 v189, v117, v125, s[98:99]
	v_cndmask_b32_e64 v196, v118, v126, s[98:99]
	v_cndmask_b32_e64 v197, v119, v127, s[98:99]
	v_cndmask_b32_e64 v200, v112, v120, s[98:99]
	v_cndmask_b32_e64 v201, v113, v121, s[98:99]
	v_cndmask_b32_e64 v204, v114, v122, s[98:99]
	v_cndmask_b32_e64 v205, v115, v123, s[98:99]
	v_fmac_f32_dpp v220, v188, v132 row_ror:1 row_mask:0xf bank_mask:0xf
	v_fmac_f32_dpp v221, v189, v133 row_ror:1 row_mask:0xf bank_mask:0xf
	v_fmac_f32_dpp v222, v196, v134 row_ror:1 row_mask:0xf bank_mask:0xf
	v_fmac_f32_dpp v223, v197, v135 row_ror:1 row_mask:0xf bank_mask:0xf
	v_fmac_f32_dpp v224, v200, v148 row_ror:1 row_mask:0xf bank_mask:0xf
	v_fmac_f32_dpp v225, v201, v149 row_ror:1 row_mask:0xf bank_mask:0xf
	v_fmac_f32_dpp v226, v204, v150 row_ror:1 row_mask:0xf bank_mask:0xf
	v_fmac_f32_dpp v227, v205, v151 row_ror:1 row_mask:0xf bank_mask:0xf
	v_cndmask_b32_e64 v188, v124, v116, s[40:41]
	v_cndmask_b32_e64 v189, v125, v117, s[40:41]
	v_cndmask_b32_e64 v196, v126, v118, s[40:41]
	v_cndmask_b32_e64 v197, v127, v119, s[40:41]
	v_cndmask_b32_e64 v200, v120, v112, s[40:41]
	v_cndmask_b32_e64 v201, v121, v113, s[40:41]
	v_cndmask_b32_e64 v204, v122, v114, s[40:41]
	v_cndmask_b32_e64 v205, v123, v115, s[40:41]
	v_fmac_f32_dpp v220, v188, v128 row_ror:2 row_mask:0xf bank_mask:0xf
	v_fmac_f32_dpp v221, v189, v129 row_ror:2 row_mask:0xf bank_mask:0xf
	v_fmac_f32_dpp v222, v196, v130 row_ror:2 row_mask:0xf bank_mask:0xf
	v_fmac_f32_dpp v223, v197, v131 row_ror:2 row_mask:0xf bank_mask:0xf
	v_fmac_f32_dpp v224, v200, v144 row_ror:2 row_mask:0xf bank_mask:0xf
	v_fmac_f32_dpp v225, v201, v145 row_ror:2 row_mask:0xf bank_mask:0xf
	v_fmac_f32_dpp v226, v204, v146 row_ror:2 row_mask:0xf bank_mask:0xf
	v_fmac_f32_dpp v227, v205, v147 row_ror:2 row_mask:0xf bank_mask:0xf
	v_pk_mul_f32 v[190:191], v[220:221], s[100:101] op_sel_hi:[1,0]
	v_pk_mul_f32 v[250:251], v[222:223], s[100:101] op_sel_hi:[1,0]
	v_exp_f32_e32 v190, v190
	v_exp_f32_e32 v191, v191
	v_exp_f32_e32 v250, v250
	v_exp_f32_e32 v251, v251
	v_pk_mul_f32 v[220:221], v[220:221], v[224:225]
	v_pk_mul_f32 v[222:223], v[222:223], v[226:227]
	v_pk_add_f32 v[190:191], v[190:191], 1.0 op_sel_hi:[1,0]
	v_pk_add_f32 v[250:251], v[250:251], 1.0 op_sel_hi:[1,0]
	v_rcp_f32_e32 v190, v190
	v_rcp_f32_e32 v191, v191
	v_rcp_f32_e32 v250, v250
	v_rcp_f32_e32 v251, v251
	v_pk_mul_f32 v[220:221], v[220:221], v[190:191]
	v_pk_mul_f32 v[222:223], v[222:223], v[250:251]
	v_cvt_pk_bf16_f32 v194, v220, v221
	v_cvt_pk_bf16_f32 v195, v222, v223
	v_pk_fma_f32 v[220:221], v[136:137], v[108:109], v[140:141]
	v_pk_fma_f32 v[222:223], v[138:139], v[110:111], v[142:143]
	v_pk_fma_f32 v[224:225], v[152:153], v[104:105], v[156:157]
	v_pk_fma_f32 v[226:227], v[154:155], v[106:107], v[158:159]
	v_cndmask_b32_e64 v188, v108, v116, s[98:99]
	v_cndmask_b32_e64 v189, v109, v117, s[98:99]
	v_cndmask_b32_e64 v196, v110, v118, s[98:99]
	v_cndmask_b32_e64 v197, v111, v119, s[98:99]
	v_cndmask_b32_e64 v200, v104, v112, s[98:99]
	v_cndmask_b32_e64 v201, v105, v113, s[98:99]
	v_cndmask_b32_e64 v204, v106, v114, s[98:99]
	v_cndmask_b32_e64 v205, v107, v115, s[98:99]
	v_fmac_f32_dpp v220, v188, v132 row_ror:1 row_mask:0xf bank_mask:0xf
	v_fmac_f32_dpp v221, v189, v133 row_ror:1 row_mask:0xf bank_mask:0xf
	v_fmac_f32_dpp v222, v196, v134 row_ror:1 row_mask:0xf bank_mask:0xf
	v_fmac_f32_dpp v223, v197, v135 row_ror:1 row_mask:0xf bank_mask:0xf
	v_fmac_f32_dpp v224, v200, v148 row_ror:1 row_mask:0xf bank_mask:0xf
	v_fmac_f32_dpp v225, v201, v149 row_ror:1 row_mask:0xf bank_mask:0xf
	v_fmac_f32_dpp v226, v204, v150 row_ror:1 row_mask:0xf bank_mask:0xf
	v_fmac_f32_dpp v227, v205, v151 row_ror:1 row_mask:0xf bank_mask:0xf
	v_cndmask_b32_e64 v188, v116, v108, s[40:41]
	v_cndmask_b32_e64 v189, v117, v109, s[40:41]
	v_cndmask_b32_e64 v196, v118, v110, s[40:41]
	v_cndmask_b32_e64 v197, v119, v111, s[40:41]
	v_cndmask_b32_e64 v200, v112, v104, s[40:41]
	v_cndmask_b32_e64 v201, v113, v105, s[40:41]
	v_cndmask_b32_e64 v204, v114, v106, s[40:41]
	v_cndmask_b32_e64 v205, v115, v107, s[40:41]
	v_fmac_f32_dpp v220, v188, v128 row_ror:2 row_mask:0xf bank_mask:0xf
	v_fmac_f32_dpp v221, v189, v129 row_ror:2 row_mask:0xf bank_mask:0xf
	v_fmac_f32_dpp v222, v196, v130 row_ror:2 row_mask:0xf bank_mask:0xf
	v_fmac_f32_dpp v223, v197, v131 row_ror:2 row_mask:0xf bank_mask:0xf
	v_fmac_f32_dpp v224, v200, v144 row_ror:2 row_mask:0xf bank_mask:0xf
	v_fmac_f32_dpp v225, v201, v145 row_ror:2 row_mask:0xf bank_mask:0xf
	v_fmac_f32_dpp v226, v204, v146 row_ror:2 row_mask:0xf bank_mask:0xf
	v_fmac_f32_dpp v227, v205, v147 row_ror:2 row_mask:0xf bank_mask:0xf
	v_pk_mul_f32 v[190:191], v[220:221], s[100:101] op_sel_hi:[1,0]
	v_pk_mul_f32 v[250:251], v[222:223], s[100:101] op_sel_hi:[1,0]
	v_exp_f32_e32 v190, v190
	v_exp_f32_e32 v191, v191
	v_exp_f32_e32 v250, v250
	v_exp_f32_e32 v251, v251
	v_pk_mul_f32 v[220:221], v[220:221], v[224:225]
	v_pk_mul_f32 v[222:223], v[222:223], v[226:227]
	v_pk_add_f32 v[190:191], v[190:191], 1.0 op_sel_hi:[1,0]
	v_pk_add_f32 v[250:251], v[250:251], 1.0 op_sel_hi:[1,0]
	v_rcp_f32_e32 v190, v190
	v_rcp_f32_e32 v191, v191
	v_rcp_f32_e32 v250, v250
	v_rcp_f32_e32 v251, v251
	v_pk_mul_f32 v[220:221], v[220:221], v[190:191]
	v_pk_mul_f32 v[222:223], v[222:223], v[250:251]
	v_cvt_pk_bf16_f32 v198, v220, v221
	v_cvt_pk_bf16_f32 v199, v222, v223
; #define PG8_LAS __attribute__((address_space(3)))
;     __device__ __forceinline__ void operator()(const f32x4 (&acc)[2][2][4][2], const Unit& u, int wr, int wc, int fr, int fq) const {
;     ...
;                 for (int bj = 0; bj < 2; ++bj) { const int col = bj * FF + gcol + 4;
;                     w0[bj] = *(const f32x4*)(cw + col); w1[bj] = *(const f32x4*)(cw + FF2 + col); w2[bj] = *(const f32x4*)(cw + 2 * FF2 + col); bb[bj] = *(const f32x4*)(cb + col); } }
; #pragma unroll
;             for (int ai = 0; ai < 2; ++ai) {
;                 f32x4 pg[2]; const int pb = ai * 2 + wr - 1;
; #pragma unroll
;                 for (int bj = 0; bj < 2; ++bj) { pg[bj] = (f32x4){0.f, 0.f, 0.f, 0.f};
;                     if (pb >= 0 && fr >= 14) pg[bj] = *(const PG8_LAS f32x4*)(halo + (pb * 2 + (fr - 14)) * 256 + bj * HALF + lcol + 4 * n); }
; #pragma unroll
;                 for (int m = 0; m < 4; ++m) {
;                     f32x4 cur[2], h[2];
; #pragma unroll
;                     for (int bj = 0; bj < 2; ++bj) { cur[bj] = acc[ai][bj][m][n] * rs[ai][m]; f32x4 x1, x2;
; #pragma unroll
;                         for (int e = 0; e < 4; ++e) { const float c1 = dpp_ror1(cur[bj][e]), p1 = dpp_ror1(pg[bj][e]), c2 = dpp_ror2(cur[bj][e]), p2 = dpp_ror2(pg[bj][e]);
;                             x1[e] = fr >= 1 ? c1 : p1; x2[e] = fr >= 2 ? c2 : p2; }
;                         h[bj] = bb[bj] + w0[bj] * x2 + w1[bj] * x1 + w2[bj] * cur[bj]; }
;                     if (ai == 0 && wr == 0 && m == 0 && fr < 2) {
;                         *(f32x4*)(hc0 + (size_t)(u.pm * 2 + fr) * FF2 + gcol + 4 * n) = h[0]; *(f32x4*)(hc0 + (size_t)(u.pm * 2 + fr) * FF2 + FF + gcol + 4 * n) = h[1]; }
;                     f32x4 a;
; #pragma unroll
;                     for (int e = 0; e < 4; ++e) { const float g = h[0][e]; a[e] = g * __builtin_amdgcn_rcpf(1.0f + __builtin_amdgcn_exp2f(-1.4426950408889634f * g)) * h[1][e]; }
;                     const unsigned p0 = cvt_pk_bf16(a[0], a[1]), p1 = cvt_pk_bf16(a[2], a[3]);
;                     if (n == 0) { pk_lo[ai][m][0] = p0; pk_lo[ai][m][1] = p1; }
;                     else { u32x4 w; w.x = pk_lo[ai][m][0]; w.y = pk_lo[ai][m][1]; w.z = p0; w.w = p1;
;                         *(u32x4*)(act + (size_t)(u.pm * BM + ai * HALF + wr * 64 + m * 16 + fr) * FF + gcol) = w; }
	v_pk_fma_f32 v[220:221], v[136:137], v[100:101], v[140:141]
	v_pk_fma_f32 v[222:223], v[138:139], v[102:103], v[142:143]
	v_pk_fma_f32 v[224:225], v[152:153], v[96:97], v[156:157]
	v_pk_fma_f32 v[226:227], v[154:155], v[98:99], v[158:159]
	v_cndmask_b32_e64 v188, v100, v108, s[98:99]
	v_cndmask_b32_e64 v189, v101, v109, s[98:99]
	v_cndmask_b32_e64 v196, v102, v110, s[98:99]
	v_cndmask_b32_e64 v197, v103, v111, s[98:99]
	v_cndmask_b32_e64 v200, v96, v104, s[98:99]
	v_cndmask_b32_e64 v201, v97, v105, s[98:99]
	v_cndmask_b32_e64 v204, v98, v106, s[98:99]
	v_cndmask_b32_e64 v205, v99, v107, s[98:99]
	v_fmac_f32_dpp v220, v188, v132 row_ror:1 row_mask:0xf bank_mask:0xf
	v_fmac_f32_dpp v221, v189, v133 row_ror:1 row_mask:0xf bank_mask:0xf
	v_fmac_f32_dpp v222, v196, v134 row_ror:1 row_mask:0xf bank_mask:0xf
	v_fmac_f32_dpp v223, v197, v135 row_ror:1 row_mask:0xf bank_mask:0xf
	v_fmac_f32_dpp v224, v200, v148 row_ror:1 row_mask:0xf bank_mask:0xf
	v_fmac_f32_dpp v225, v201, v149 row_ror:1 row_mask:0xf bank_mask:0xf
	v_fmac_f32_dpp v226, v204, v150 row_ror:1 row_mask:0xf bank_mask:0xf
	v_fmac_f32_dpp v227, v205, v151 row_ror:1 row_mask:0xf bank_mask:0xf
	v_cndmask_b32_e64 v188, v108, v100, s[40:41]
	v_cndmask_b32_e64 v189, v109, v101, s[40:41]
	v_cndmask_b32_e64 v196, v110, v102, s[40:41]
	v_cndmask_b32_e64 v197, v111, v103, s[40:41]
	v_cndmask_b32_e64 v200, v104, v96, s[40:41]
	v_cndmask_b32_e64 v201, v105, v97, s[40:41]
	v_cndmask_b32_e64 v204, v106, v98, s[40:41]
	v_cndmask_b32_e64 v205, v107, v99, s[40:41]
	v_fmac_f32_dpp v220, v188, v128 row_ror:2 row_mask:0xf bank_mask:0xf
	v_fmac_f32_dpp v221, v189, v129 row_ror:2 row_mask:0xf bank_mask:0xf
	v_fmac_f32_dpp v222, v196, v130 row_ror:2 row_mask:0xf bank_mask:0xf
	v_fmac_f32_dpp v223, v197, v131 row_ror:2 row_mask:0xf bank_mask:0xf
	v_fmac_f32_dpp v224, v200, v144 row_ror:2 row_mask:0xf bank_mask:0xf
	v_fmac_f32_dpp v225, v201, v145 row_ror:2 row_mask:0xf bank_mask:0xf
	v_fmac_f32_dpp v226, v204, v146 row_ror:2 row_mask:0xf bank_mask:0xf
	v_fmac_f32_dpp v227, v205, v147 row_ror:2 row_mask:0xf bank_mask:0xf
	v_pk_mul_f32 v[190:191], v[220:221], s[100:101] op_sel_hi:[1,0]
	v_pk_mul_f32 v[250:251], v[222:223], s[100:101] op_sel_hi:[1,0]
	v_exp_f32_e32 v190, v190
	v_exp_f32_e32 v191, v191
	v_exp_f32_e32 v250, v250
	v_exp_f32_e32 v251, v251
	v_pk_mul_f32 v[220:221], v[220:221], v[224:225]
	v_pk_mul_f32 v[222:223], v[222:223], v[226:227]
	v_pk_add_f32 v[190:191], v[190:191], 1.0 op_sel_hi:[1,0]
	v_pk_add_f32 v[250:251], v[250:251], 1.0 op_sel_hi:[1,0]
	v_rcp_f32_e32 v190, v190
	v_rcp_f32_e32 v191, v191
	v_rcp_f32_e32 v250, v250
	v_rcp_f32_e32 v251, v251
	v_pk_mul_f32 v[220:221], v[220:221], v[190:191]
	v_pk_mul_f32 v[222:223], v[222:223], v[250:251]
	v_cvt_pk_bf16_f32 v202, v220, v221
	v_cvt_pk_bf16_f32 v203, v222, v223
	global_load_dwordx4 v[124:127], v233, s[14:15] offset:16
	global_load_dwordx4 v[116:119], v233, s[16:17] offset:16
	global_load_dwordx4 v[108:111], v233, s[92:93] offset:16
	global_load_dwordx4 v[100:103], v233, s[60:61] offset:16
	global_load_dwordx4 v[120:123], v235, s[14:15] offset:16
	global_load_dwordx4 v[112:115], v235, s[16:17] offset:16
	global_load_dwordx4 v[104:107], v235, s[92:93] offset:16
	global_load_dwordx4 v[96:99], v235, s[60:61] offset:16
	v_pk_fma_f32 v[220:221], v[136:137], v[92:93], v[140:141]
	v_pk_fma_f32 v[222:223], v[138:139], v[94:95], v[142:143]
	v_pk_fma_f32 v[224:225], v[152:153], v[88:89], v[156:157]
	v_pk_fma_f32 v[226:227], v[154:155], v[90:91], v[158:159]
	v_cndmask_b32_e64 v188, v92, v178, s[98:99]
	v_cndmask_b32_e64 v189, v93, v179, s[98:99]
	v_cndmask_b32_e64 v196, v94, v180, s[98:99]
	v_cndmask_b32_e64 v197, v95, v181, s[98:99]
	v_cndmask_b32_e64 v200, v88, v182, s[98:99]
	v_cndmask_b32_e64 v201, v89, v183, s[98:99]
	v_cndmask_b32_e64 v204, v90, v184, s[98:99]
	v_cndmask_b32_e64 v205, v91, v185, s[98:99]
	v_fmac_f32_dpp v220, v188, v132 row_ror:1 row_mask:0xf bank_mask:0xf
	v_fmac_f32_dpp v221, v189, v133 row_ror:1 row_mask:0xf bank_mask:0xf
	v_fmac_f32_dpp v222, v196, v134 row_ror:1 row_mask:0xf bank_mask:0xf
	v_fmac_f32_dpp v223, v197, v135 row_ror:1 row_mask:0xf bank_mask:0xf
	v_fmac_f32_dpp v224, v200, v148 row_ror:1 row_mask:0xf bank_mask:0xf
	v_fmac_f32_dpp v225, v201, v149 row_ror:1 row_mask:0xf bank_mask:0xf
	v_fmac_f32_dpp v226, v204, v150 row_ror:1 row_mask:0xf bank_mask:0xf
	v_fmac_f32_dpp v227, v205, v151 row_ror:1 row_mask:0xf bank_mask:0xf
	v_cndmask_b32_e64 v188, v178, v92, s[40:41]
	v_cndmask_b32_e64 v189, v179, v93, s[40:41]
	v_cndmask_b32_e64 v196, v180, v94, s[40:41]
	v_cndmask_b32_e64 v197, v181, v95, s[40:41]
	v_cndmask_b32_e64 v200, v182, v88, s[40:41]
	v_cndmask_b32_e64 v201, v183, v89, s[40:41]
	v_cndmask_b32_e64 v204, v184, v90, s[40:41]
	v_cndmask_b32_e64 v205, v185, v91, s[40:41]
	v_fmac_f32_dpp v220, v188, v128 row_ror:2 row_mask:0xf bank_mask:0xf
	v_fmac_f32_dpp v221, v189, v129 row_ror:2 row_mask:0xf bank_mask:0xf
	v_fmac_f32_dpp v222, v196, v130 row_ror:2 row_mask:0xf bank_mask:0xf
	v_fmac_f32_dpp v223, v197, v131 row_ror:2 row_mask:0xf bank_mask:0xf
	v_fmac_f32_dpp v224, v200, v144 row_ror:2 row_mask:0xf bank_mask:0xf
	v_fmac_f32_dpp v225, v201, v145 row_ror:2 row_mask:0xf bank_mask:0xf
	v_fmac_f32_dpp v226, v204, v146 row_ror:2 row_mask:0xf bank_mask:0xf
	v_fmac_f32_dpp v227, v205, v147 row_ror:2 row_mask:0xf bank_mask:0xf
	v_pk_mul_f32 v[190:191], v[220:221], s[100:101] op_sel_hi:[1,0]
	v_pk_mul_f32 v[250:251], v[222:223], s[100:101] op_sel_hi:[1,0]
	v_exp_f32_e32 v190, v190
	v_exp_f32_e32 v191, v191
	v_exp_f32_e32 v250, v250
	v_exp_f32_e32 v251, v251
	v_pk_mul_f32 v[220:221], v[220:221], v[224:225]
; #define PG8_LAS __attribute__((address_space(3)))
; __device__ __forceinline__ unsigned cvt_pk_bf16(float lo, float hi) { unsigned r; asm volatile("v_cvt_pk_bf16_f32 %0, %1, %2" : "=v"(r) : "v"(lo), "v"(hi)); return r; }
; __device__ __forceinline__ float dpp_ror1(float x) { return __int_as_float(__builtin_amdgcn_update_dpp(0, __float_as_int(x), 0x121, 0xf, 0xf, false)); }
;     __device__ __forceinline__ void operator()(const f32x4 (&acc)[2][2][4][2], const Unit& u, int wr, int wc, int fr, int fq) const {
;     ...
;             for (int ai = 0; ai < 2; ++ai) {
;                 f32x4 pg[2]; const int pb = ai * 2 + wr - 1;
; #pragma unroll
;                 for (int bj = 0; bj < 2; ++bj) { pg[bj] = (f32x4){0.f, 0.f, 0.f, 0.f};
;                     if (pb >= 0 && fr >= 14) pg[bj] = *(const PG8_LAS f32x4*)(halo + (pb * 2 + (fr - 14)) * 256 + bj * HALF + lcol + 4 * n); }
;     ...
;                 for (int m = 0; m < 4; ++m) {
;                     f32x4 cur[2], h[2];
; #pragma unroll
;                     for (int bj = 0; bj < 2; ++bj) { cur[bj] = acc[ai][bj][m][n] * rs[ai][m]; f32x4 x1, x2;
; #pragma unroll
;                         for (int e = 0; e < 4; ++e) { const float c1 = dpp_ror1(cur[bj][e]), p1 = dpp_ror1(pg[bj][e]), c2 = dpp_ror2(cur[bj][e]), p2 = dpp_ror2(pg[bj][e]);
;                             x1[e] = fr >= 1 ? c1 : p1; x2[e] = fr >= 2 ? c2 : p2; }
;                         h[bj] = bb[bj] + w0[bj] * x2 + w1[bj] * x1 + w2[bj] * cur[bj]; }
;                     if (ai == 0 && wr == 0 && m == 0 && fr < 2) {
;                         *(f32x4*)(hc0 + (size_t)(u.pm * 2 + fr) * FF2 + gcol + 4 * n) = h[0]; *(f32x4*)(hc0 + (size_t)(u.pm * 2 + fr) * FF2 + FF + gcol + 4 * n) = h[1]; }
;                     f32x4 a;
; #pragma unroll
;                     for (int e = 0; e < 4; ++e) { const float g = h[0][e]; a[e] = g * __builtin_amdgcn_rcpf(1.0f + __builtin_amdgcn_exp2f(-1.4426950408889634f * g)) * h[1][e]; }
;                     const unsigned p0 = cvt_pk_bf16(a[0], a[1]), p1 = cvt_pk_bf16(a[2], a[3]);
;                     if (n == 0) { pk_lo[ai][m][0] = p0; pk_lo[ai][m][1] = p1; }
;                     else { u32x4 w; w.x = pk_lo[ai][m][0]; w.y = pk_lo[ai][m][1]; w.z = p0; w.w = p1;
;                         *(u32x4*)(act + (size_t)(u.pm * BM + ai * HALF + wr * 64 + m * 16 + fr) * FF + gcol) = w; }
	v_pk_mul_f32 v[222:223], v[222:223], v[226:227]
	v_pk_add_f32 v[190:191], v[190:191], 1.0 op_sel_hi:[1,0]
	v_pk_add_f32 v[250:251], v[250:251], 1.0 op_sel_hi:[1,0]
	v_rcp_f32_e32 v190, v190
	v_rcp_f32_e32 v191, v191
	v_rcp_f32_e32 v250, v250
	v_rcp_f32_e32 v251, v251
	v_pk_mul_f32 v[220:221], v[220:221], v[190:191]
	v_pk_mul_f32 v[222:223], v[222:223], v[250:251]
	v_cvt_pk_bf16_f32 v160, v220, v221
	v_cvt_pk_bf16_f32 v161, v222, v223
	v_pk_fma_f32 v[220:221], v[136:137], v[84:85], v[140:141]
	v_pk_fma_f32 v[222:223], v[138:139], v[86:87], v[142:143]
	v_pk_fma_f32 v[224:225], v[152:153], v[80:81], v[156:157]
	v_pk_fma_f32 v[226:227], v[154:155], v[82:83], v[158:159]
	v_cndmask_b32_e64 v188, v84, v92, s[98:99]
	v_cndmask_b32_e64 v189, v85, v93, s[98:99]
	v_cndmask_b32_e64 v196, v86, v94, s[98:99]
	v_cndmask_b32_e64 v197, v87, v95, s[98:99]
	v_cndmask_b32_e64 v200, v80, v88, s[98:99]
	v_cndmask_b32_e64 v201, v81, v89, s[98:99]
	v_cndmask_b32_e64 v204, v82, v90, s[98:99]
	v_cndmask_b32_e64 v205, v83, v91, s[98:99]
	v_fmac_f32_dpp v220, v188, v132 row_ror:1 row_mask:0xf bank_mask:0xf
	v_fmac_f32_dpp v221, v189, v133 row_ror:1 row_mask:0xf bank_mask:0xf
	v_fmac_f32_dpp v222, v196, v134 row_ror:1 row_mask:0xf bank_mask:0xf
	v_fmac_f32_dpp v223, v197, v135 row_ror:1 row_mask:0xf bank_mask:0xf
	v_fmac_f32_dpp v224, v200, v148 row_ror:1 row_mask:0xf bank_mask:0xf
	v_fmac_f32_dpp v225, v201, v149 row_ror:1 row_mask:0xf bank_mask:0xf
	v_fmac_f32_dpp v226, v204, v150 row_ror:1 row_mask:0xf bank_mask:0xf
	v_fmac_f32_dpp v227, v205, v151 row_ror:1 row_mask:0xf bank_mask:0xf
	v_cndmask_b32_e64 v188, v92, v84, s[40:41]
	v_cndmask_b32_e64 v189, v93, v85, s[40:41]
	v_cndmask_b32_e64 v196, v94, v86, s[40:41]
	v_cndmask_b32_e64 v197, v95, v87, s[40:41]
	v_cndmask_b32_e64 v200, v88, v80, s[40:41]
	v_cndmask_b32_e64 v201, v89, v81, s[40:41]
	v_cndmask_b32_e64 v204, v90, v82, s[40:41]
	v_cndmask_b32_e64 v205, v91, v83, s[40:41]
	v_fmac_f32_dpp v220, v188, v128 row_ror:2 row_mask:0xf bank_mask:0xf
	v_fmac_f32_dpp v221, v189, v129 row_ror:2 row_mask:0xf bank_mask:0xf
	v_fmac_f32_dpp v222, v196, v130 row_ror:2 row_mask:0xf bank_mask:0xf
	v_fmac_f32_dpp v223, v197, v131 row_ror:2 row_mask:0xf bank_mask:0xf
	v_fmac_f32_dpp v224, v200, v144 row_ror:2 row_mask:0xf bank_mask:0xf
	v_fmac_f32_dpp v225, v201, v145 row_ror:2 row_mask:0xf bank_mask:0xf
	v_fmac_f32_dpp v226, v204, v146 row_ror:2 row_mask:0xf bank_mask:0xf
	v_fmac_f32_dpp v227, v205, v147 row_ror:2 row_mask:0xf bank_mask:0xf
	v_pk_mul_f32 v[190:191], v[220:221], s[100:101] op_sel_hi:[1,0]
	v_pk_mul_f32 v[250:251], v[222:223], s[100:101] op_sel_hi:[1,0]
	v_exp_f32_e32 v190, v190
	v_exp_f32_e32 v191, v191
	v_exp_f32_e32 v250, v250
	v_exp_f32_e32 v251, v251
	v_pk_mul_f32 v[220:221], v[220:221], v[224:225]
	v_pk_mul_f32 v[222:223], v[222:223], v[226:227]
	v_pk_add_f32 v[190:191], v[190:191], 1.0 op_sel_hi:[1,0]
	v_pk_add_f32 v[250:251], v[250:251], 1.0 op_sel_hi:[1,0]
	v_rcp_f32_e32 v190, v190
	v_rcp_f32_e32 v191, v191
	v_rcp_f32_e32 v250, v250
	v_rcp_f32_e32 v251, v251
	v_pk_mul_f32 v[220:221], v[220:221], v[190:191]
	v_pk_mul_f32 v[222:223], v[222:223], v[250:251]
	v_cvt_pk_bf16_f32 v164, v220, v221
	v_cvt_pk_bf16_f32 v165, v222, v223
	v_pk_fma_f32 v[220:221], v[136:137], v[76:77], v[140:141]
	v_pk_fma_f32 v[222:223], v[138:139], v[78:79], v[142:143]
	v_pk_fma_f32 v[224:225], v[152:153], v[72:73], v[156:157]
	v_pk_fma_f32 v[226:227], v[154:155], v[74:75], v[158:159]
	v_cndmask_b32_e64 v188, v76, v84, s[98:99]
	v_cndmask_b32_e64 v189, v77, v85, s[98:99]
	v_cndmask_b32_e64 v196, v78, v86, s[98:99]
	v_cndmask_b32_e64 v197, v79, v87, s[98:99]
	v_cndmask_b32_e64 v200, v72, v80, s[98:99]
	v_cndmask_b32_e64 v201, v73, v81, s[98:99]
	v_cndmask_b32_e64 v204, v74, v82, s[98:99]
	v_cndmask_b32_e64 v205, v75, v83, s[98:99]
	v_fmac_f32_dpp v220, v188, v132 row_ror:1 row_mask:0xf bank_mask:0xf
	v_fmac_f32_dpp v221, v189, v133 row_ror:1 row_mask:0xf bank_mask:0xf
	v_fmac_f32_dpp v222, v196, v134 row_ror:1 row_mask:0xf bank_mask:0xf
	v_fmac_f32_dpp v223, v197, v135 row_ror:1 row_mask:0xf bank_mask:0xf
	v_fmac_f32_dpp v224, v200, v148 row_ror:1 row_mask:0xf bank_mask:0xf
	v_fmac_f32_dpp v225, v201, v149 row_ror:1 row_mask:0xf bank_mask:0xf
	v_fmac_f32_dpp v226, v204, v150 row_ror:1 row_mask:0xf bank_mask:0xf
	v_fmac_f32_dpp v227, v205, v151 row_ror:1 row_mask:0xf bank_mask:0xf
	v_cndmask_b32_e64 v188, v84, v76, s[40:41]
	v_cndmask_b32_e64 v189, v85, v77, s[40:41]
	v_cndmask_b32_e64 v196, v86, v78, s[40:41]
	v_cndmask_b32_e64 v197, v87, v79, s[40:41]
	v_cndmask_b32_e64 v200, v80, v72, s[40:41]
	v_cndmask_b32_e64 v201, v81, v73, s[40:41]
	v_cndmask_b32_e64 v204, v82, v74, s[40:41]
	v_cndmask_b32_e64 v205, v83, v75, s[40:41]
	v_fmac_f32_dpp v220, v188, v128 row_ror:2 row_mask:0xf bank_mask:0xf
	v_fmac_f32_dpp v221, v189, v129 row_ror:2 row_mask:0xf bank_mask:0xf
	v_fmac_f32_dpp v222, v196, v130 row_ror:2 row_mask:0xf bank_mask:0xf
	v_fmac_f32_dpp v223, v197, v131 row_ror:2 row_mask:0xf bank_mask:0xf
	v_fmac_f32_dpp v224, v200, v144 row_ror:2 row_mask:0xf bank_mask:0xf
	v_fmac_f32_dpp v225, v201, v145 row_ror:2 row_mask:0xf bank_mask:0xf
	v_fmac_f32_dpp v226, v204, v146 row_ror:2 row_mask:0xf bank_mask:0xf
	v_fmac_f32_dpp v227, v205, v147 row_ror:2 row_mask:0xf bank_mask:0xf
	v_pk_mul_f32 v[190:191], v[220:221], s[100:101] op_sel_hi:[1,0]
	v_pk_mul_f32 v[250:251], v[222:223], s[100:101] op_sel_hi:[1,0]
	v_exp_f32_e32 v190, v190
	v_exp_f32_e32 v191, v191
	v_exp_f32_e32 v250, v250
	v_exp_f32_e32 v251, v251
	v_pk_mul_f32 v[220:221], v[220:221], v[224:225]
	v_pk_mul_f32 v[222:223], v[222:223], v[226:227]
	v_pk_add_f32 v[190:191], v[190:191], 1.0 op_sel_hi:[1,0]
	v_pk_add_f32 v[250:251], v[250:251], 1.0 op_sel_hi:[1,0]
	v_rcp_f32_e32 v190, v190
	v_rcp_f32_e32 v191, v191
	v_rcp_f32_e32 v250, v250
	v_rcp_f32_e32 v251, v251
	v_pk_mul_f32 v[220:221], v[220:221], v[190:191]
	v_pk_mul_f32 v[222:223], v[222:223], v[250:251]
	v_cvt_pk_bf16_f32 v178, v220, v221
	v_cvt_pk_bf16_f32 v179, v222, v223
	s_and_b64 vcc, exec, s[94:95]
	s_cbranch_vccnz .Lp7_hz1
	ds_read_b128 v[92:95], v215
	ds_read_b128 v[88:91], v216
	s_branch .Lp7_hr1

; #define PG8_LAS __attribute__((address_space(3)))
; __device__ __forceinline__ unsigned cvt_pk_bf16(float lo, float hi) { unsigned r; asm volatile("v_cvt_pk_bf16_f32 %0, %1, %2" : "=v"(r) : "v"(lo), "v"(hi)); return r; }
; __device__ __forceinline__ float dpp_ror1(float x) { return __int_as_float(__builtin_amdgcn_update_dpp(0, __float_as_int(x), 0x121, 0xf, 0xf, false)); }
; __device__ __forceinline__ float dpp_ror2(float x) { return __int_as_float(__builtin_amdgcn_update_dpp(0, __float_as_int(x), 0x122, 0xf, 0xf, false)); }
;     __device__ __forceinline__ void operator()(const f32x4 (&acc)[2][2][4][2], const Unit& u, int wr, int wc, int fr, int fq) const {
;     ...
;                     if (pb >= 0 && fr >= 14) pg[bj] = *(const PG8_LAS f32x4*)(halo + (pb * 2 + (fr - 14)) * 256 + bj * HALF + lcol + 4 * n); }
; #pragma unroll
;                 for (int m = 0; m < 4; ++m) {
;                     f32x4 cur[2], h[2];
; #pragma unroll
;                     for (int bj = 0; bj < 2; ++bj) { cur[bj] = acc[ai][bj][m][n] * rs[ai][m]; f32x4 x1, x2;
; #pragma unroll
;                         for (int e = 0; e < 4; ++e) { const float c1 = dpp_ror1(cur[bj][e]), p1 = dpp_ror1(pg[bj][e]), c2 = dpp_ror2(cur[bj][e]), p2 = dpp_ror2(pg[bj][e]);
;                             x1[e] = fr >= 1 ? c1 : p1; x2[e] = fr >= 2 ? c2 : p2; }
;                         h[bj] = bb[bj] + w0[bj] * x2 + w1[bj] * x1 + w2[bj] * cur[bj]; }
;                     if (ai == 0 && wr == 0 && m == 0 && fr < 2) {
;                         *(f32x4*)(hc0 + (size_t)(u.pm * 2 + fr) * FF2 + gcol + 4 * n) = h[0]; *(f32x4*)(hc0 + (size_t)(u.pm * 2 + fr) * FF2 + FF + gcol + 4 * n) = h[1]; }
;                     f32x4 a;
; #pragma unroll
;                     for (int e = 0; e < 4; ++e) { const float g = h[0][e]; a[e] = g * __builtin_amdgcn_rcpf(1.0f + __builtin_amdgcn_exp2f(-1.4426950408889634f * g)) * h[1][e]; }
;                     const unsigned p0 = cvt_pk_bf16(a[0], a[1]), p1 = cvt_pk_bf16(a[2], a[3]);
;                     if (n == 0) { pk_lo[ai][m][0] = p0; pk_lo[ai][m][1] = p1; }
;                     else { u32x4 w; w.x = pk_lo[ai][m][0]; w.y = pk_lo[ai][m][1]; w.z = p0; w.w = p1;
;                         *(u32x4*)(act + (size_t)(u.pm * BM + ai * HALF + wr * 64 + m * 16 + fr) * FF + gcol) = w; }
.Lp7_hr1:
	ds_read_b128 v[84:87], v217
	ds_read_b128 v[80:83], v218
	v_pk_fma_f32 v[220:221], v[136:137], v[68:69], v[140:141]
	v_pk_fma_f32 v[222:223], v[138:139], v[70:71], v[142:143]
	v_pk_fma_f32 v[224:225], v[152:153], v[64:65], v[156:157]
	v_pk_fma_f32 v[226:227], v[154:155], v[66:67], v[158:159]
	v_cndmask_b32_e64 v188, v68, v76, s[98:99]
	v_cndmask_b32_e64 v189, v69, v77, s[98:99]
	v_cndmask_b32_e64 v196, v70, v78, s[98:99]
	v_cndmask_b32_e64 v197, v71, v79, s[98:99]
	v_cndmask_b32_e64 v200, v64, v72, s[98:99]
	v_cndmask_b32_e64 v201, v65, v73, s[98:99]
	v_cndmask_b32_e64 v204, v66, v74, s[98:99]
	v_cndmask_b32_e64 v205, v67, v75, s[98:99]
	v_fmac_f32_dpp v220, v188, v132 row_ror:1 row_mask:0xf bank_mask:0xf
	v_fmac_f32_dpp v221, v189, v133 row_ror:1 row_mask:0xf bank_mask:0xf
	v_fmac_f32_dpp v222, v196, v134 row_ror:1 row_mask:0xf bank_mask:0xf
	v_fmac_f32_dpp v223, v197, v135 row_ror:1 row_mask:0xf bank_mask:0xf
	v_fmac_f32_dpp v224, v200, v148 row_ror:1 row_mask:0xf bank_mask:0xf
	v_fmac_f32_dpp v225, v201, v149 row_ror:1 row_mask:0xf bank_mask:0xf
	v_fmac_f32_dpp v226, v204, v150 row_ror:1 row_mask:0xf bank_mask:0xf
	v_fmac_f32_dpp v227, v205, v151 row_ror:1 row_mask:0xf bank_mask:0xf
	v_cndmask_b32_e64 v188, v76, v68, s[40:41]
	v_cndmask_b32_e64 v189, v77, v69, s[40:41]
	v_cndmask_b32_e64 v196, v78, v70, s[40:41]
	v_cndmask_b32_e64 v197, v79, v71, s[40:41]
	v_cndmask_b32_e64 v200, v72, v64, s[40:41]
	v_cndmask_b32_e64 v201, v73, v65, s[40:41]
	v_cndmask_b32_e64 v204, v74, v66, s[40:41]
	v_cndmask_b32_e64 v205, v75, v67, s[40:41]
	v_fmac_f32_dpp v220, v188, v128 row_ror:2 row_mask:0xf bank_mask:0xf
	v_fmac_f32_dpp v221, v189, v129 row_ror:2 row_mask:0xf bank_mask:0xf
	v_fmac_f32_dpp v222, v196, v130 row_ror:2 row_mask:0xf bank_mask:0xf
	v_fmac_f32_dpp v223, v197, v131 row_ror:2 row_mask:0xf bank_mask:0xf
	v_fmac_f32_dpp v224, v200, v144 row_ror:2 row_mask:0xf bank_mask:0xf
	v_fmac_f32_dpp v225, v201, v145 row_ror:2 row_mask:0xf bank_mask:0xf
	v_fmac_f32_dpp v226, v204, v146 row_ror:2 row_mask:0xf bank_mask:0xf
	v_fmac_f32_dpp v227, v205, v147 row_ror:2 row_mask:0xf bank_mask:0xf
	v_pk_mul_f32 v[190:191], v[220:221], s[100:101] op_sel_hi:[1,0]
	v_pk_mul_f32 v[250:251], v[222:223], s[100:101] op_sel_hi:[1,0]
	v_exp_f32_e32 v190, v190
	v_exp_f32_e32 v191, v191
	v_exp_f32_e32 v250, v250
	v_exp_f32_e32 v251, v251
	v_pk_mul_f32 v[220:221], v[220:221], v[224:225]
	v_pk_mul_f32 v[222:223], v[222:223], v[226:227]
	v_pk_add_f32 v[190:191], v[190:191], 1.0 op_sel_hi:[1,0]
	v_pk_add_f32 v[250:251], v[250:251], 1.0 op_sel_hi:[1,0]
	v_rcp_f32_e32 v190, v190
	v_rcp_f32_e32 v191, v191
	v_rcp_f32_e32 v250, v250
	v_rcp_f32_e32 v251, v251
	v_pk_mul_f32 v[220:221], v[220:221], v[190:191]
	v_pk_mul_f32 v[222:223], v[222:223], v[250:251]
	v_cvt_pk_bf16_f32 v182, v220, v221
	v_cvt_pk_bf16_f32 v183, v222, v223
	s_waitcnt vmcnt(0) lgkmcnt(0)
	v_pk_fma_f32 v[220:221], v[108:109], v[60:61], v[100:101]
	v_pk_fma_f32 v[222:223], v[110:111], v[62:63], v[102:103]
	v_pk_fma_f32 v[224:225], v[104:105], v[56:57], v[96:97]
	v_pk_fma_f32 v[226:227], v[106:107], v[58:59], v[98:99]
	v_cndmask_b32_e64 v72, v60, v92, s[98:99]
	v_cndmask_b32_e64 v73, v61, v93, s[98:99]
	v_cndmask_b32_e64 v74, v62, v94, s[98:99]
	v_cndmask_b32_e64 v75, v63, v95, s[98:99]
	v_cndmask_b32_e64 v76, v56, v88, s[98:99]
	v_cndmask_b32_e64 v77, v57, v89, s[98:99]
	v_cndmask_b32_e64 v78, v58, v90, s[98:99]
	v_cndmask_b32_e64 v79, v59, v91, s[98:99]
	v_fmac_f32_dpp v220, v72, v116 row_ror:1 row_mask:0xf bank_mask:0xf
	v_fmac_f32_dpp v221, v73, v117 row_ror:1 row_mask:0xf bank_mask:0xf
	v_fmac_f32_dpp v222, v74, v118 row_ror:1 row_mask:0xf bank_mask:0xf
	v_fmac_f32_dpp v223, v75, v119 row_ror:1 row_mask:0xf bank_mask:0xf
	v_fmac_f32_dpp v224, v76, v112 row_ror:1 row_mask:0xf bank_mask:0xf
	v_fmac_f32_dpp v225, v77, v113 row_ror:1 row_mask:0xf bank_mask:0xf
	v_fmac_f32_dpp v226, v78, v114 row_ror:1 row_mask:0xf bank_mask:0xf
	v_fmac_f32_dpp v227, v79, v115 row_ror:1 row_mask:0xf bank_mask:0xf
	v_cndmask_b32_e64 v72, v92, v60, s[40:41]
	v_cndmask_b32_e64 v73, v93, v61, s[40:41]
	v_cndmask_b32_e64 v74, v94, v62, s[40:41]
	v_cndmask_b32_e64 v75, v95, v63, s[40:41]
	v_cndmask_b32_e64 v76, v88, v56, s[40:41]
	v_cndmask_b32_e64 v77, v89, v57, s[40:41]
	v_cndmask_b32_e64 v78, v90, v58, s[40:41]
	v_cndmask_b32_e64 v79, v91, v59, s[40:41]
	v_fmac_f32_dpp v220, v72, v124 row_ror:2 row_mask:0xf bank_mask:0xf
	v_fmac_f32_dpp v221, v73, v125 row_ror:2 row_mask:0xf bank_mask:0xf
	v_fmac_f32_dpp v222, v74, v126 row_ror:2 row_mask:0xf bank_mask:0xf
	v_fmac_f32_dpp v223, v75, v127 row_ror:2 row_mask:0xf bank_mask:0xf
	v_fmac_f32_dpp v224, v76, v120 row_ror:2 row_mask:0xf bank_mask:0xf
	v_fmac_f32_dpp v225, v77, v121 row_ror:2 row_mask:0xf bank_mask:0xf
	v_fmac_f32_dpp v226, v78, v122 row_ror:2 row_mask:0xf bank_mask:0xf
	v_fmac_f32_dpp v227, v79, v123 row_ror:2 row_mask:0xf bank_mask:0xf
	s_and_saveexec_b64 s[0:1], s[12:13]
	global_store_dwordx4 v241, v[220:223], s[84:85] offset:16
	global_store_dwordx4 v249, v[224:227], s[84:85] offset:16
	s_or_b64 exec, exec, s[0:1]
	v_pk_mul_f32 v[190:191], v[220:221], s[100:101] op_sel_hi:[1,0]
	v_pk_mul_f32 v[250:251], v[222:223], s[100:101] op_sel_hi:[1,0]
	v_exp_f32_e32 v190, v190
	v_exp_f32_e32 v191, v191
	v_exp_f32_e32 v250, v250
	v_exp_f32_e32 v251, v251
	v_pk_mul_f32 v[220:221], v[220:221], v[224:225]
	v_pk_mul_f32 v[222:223], v[222:223], v[226:227]
	v_pk_add_f32 v[190:191], v[190:191], 1.0 op_sel_hi:[1,0]
	v_pk_add_f32 v[250:251], v[250:251], 1.0 op_sel_hi:[1,0]
	v_rcp_f32_e32 v190, v190
	v_rcp_f32_e32 v191, v191
	v_rcp_f32_e32 v250, v250
	v_rcp_f32_e32 v251, v251
; __device__ __forceinline__ unsigned cvt_pk_bf16(float lo, float hi) { unsigned r; asm volatile("v_cvt_pk_bf16_f32 %0, %1, %2" : "=v"(r) : "v"(lo), "v"(hi)); return r; }
; __device__ __forceinline__ float dpp_ror1(float x) { return __int_as_float(__builtin_amdgcn_update_dpp(0, __float_as_int(x), 0x121, 0xf, 0xf, false)); }
; __device__ __forceinline__ float dpp_ror2(float x) { return __int_as_float(__builtin_amdgcn_update_dpp(0, __float_as_int(x), 0x122, 0xf, 0xf, false)); }
;     __device__ __forceinline__ void operator()(const f32x4 (&acc)[2][2][4][2], const Unit& u, int wr, int wc, int fr, int fq) const {
;     ...
;                 for (int m = 0; m < 4; ++m) {
;                     f32x4 cur[2], h[2];
; #pragma unroll
;                     for (int bj = 0; bj < 2; ++bj) { cur[bj] = acc[ai][bj][m][n] * rs[ai][m]; f32x4 x1, x2;
; #pragma unroll
;                         for (int e = 0; e < 4; ++e) { const float c1 = dpp_ror1(cur[bj][e]), p1 = dpp_ror1(pg[bj][e]), c2 = dpp_ror2(cur[bj][e]), p2 = dpp_ror2(pg[bj][e]);
;                             x1[e] = fr >= 1 ? c1 : p1; x2[e] = fr >= 2 ? c2 : p2; }
;                         h[bj] = bb[bj] + w0[bj] * x2 + w1[bj] * x1 + w2[bj] * cur[bj]; }
;                     if (ai == 0 && wr == 0 && m == 0 && fr < 2) {
;                         *(f32x4*)(hc0 + (size_t)(u.pm * 2 + fr) * FF2 + gcol + 4 * n) = h[0]; *(f32x4*)(hc0 + (size_t)(u.pm * 2 + fr) * FF2 + FF + gcol + 4 * n) = h[1]; }
;                     f32x4 a;
; #pragma unroll
;                     for (int e = 0; e < 4; ++e) { const float g = h[0][e]; a[e] = g * __builtin_amdgcn_rcpf(1.0f + __builtin_amdgcn_exp2f(-1.4426950408889634f * g)) * h[1][e]; }
;                     const unsigned p0 = cvt_pk_bf16(a[0], a[1]), p1 = cvt_pk_bf16(a[2], a[3]);
;                     if (n == 0) { pk_lo[ai][m][0] = p0; pk_lo[ai][m][1] = p1; }
;                     else { u32x4 w; w.x = pk_lo[ai][m][0]; w.y = pk_lo[ai][m][1]; w.z = p0; w.w = p1;
;                         *(u32x4*)(act + (size_t)(u.pm * BM + ai * HALF + wr * 64 + m * 16 + fr) * FF + gcol) = w; }
	v_pk_mul_f32 v[220:221], v[220:221], v[190:191]
	v_pk_mul_f32 v[222:223], v[222:223], v[250:251]
	v_cvt_pk_bf16_f32 v188, v220, v221
	v_cvt_pk_bf16_f32 v189, v222, v223
	global_store_dwordx4 v239, v[186:189], s[24:25]
	v_pk_fma_f32 v[220:221], v[108:109], v[52:53], v[100:101]
	v_pk_fma_f32 v[222:223], v[110:111], v[54:55], v[102:103]
	v_pk_fma_f32 v[224:225], v[104:105], v[48:49], v[96:97]
	v_pk_fma_f32 v[226:227], v[106:107], v[50:51], v[98:99]
	v_cndmask_b32_e64 v72, v52, v60, s[98:99]
	v_cndmask_b32_e64 v73, v53, v61, s[98:99]
	v_cndmask_b32_e64 v74, v54, v62, s[98:99]
	v_cndmask_b32_e64 v75, v55, v63, s[98:99]
	v_cndmask_b32_e64 v76, v48, v56, s[98:99]
	v_cndmask_b32_e64 v77, v49, v57, s[98:99]
	v_cndmask_b32_e64 v78, v50, v58, s[98:99]
	v_cndmask_b32_e64 v79, v51, v59, s[98:99]
	v_fmac_f32_dpp v220, v72, v116 row_ror:1 row_mask:0xf bank_mask:0xf
	v_fmac_f32_dpp v221, v73, v117 row_ror:1 row_mask:0xf bank_mask:0xf
	v_fmac_f32_dpp v222, v74, v118 row_ror:1 row_mask:0xf bank_mask:0xf
	v_fmac_f32_dpp v223, v75, v119 row_ror:1 row_mask:0xf bank_mask:0xf
	v_fmac_f32_dpp v224, v76, v112 row_ror:1 row_mask:0xf bank_mask:0xf
	v_fmac_f32_dpp v225, v77, v113 row_ror:1 row_mask:0xf bank_mask:0xf
	v_fmac_f32_dpp v226, v78, v114 row_ror:1 row_mask:0xf bank_mask:0xf
	v_fmac_f32_dpp v227, v79, v115 row_ror:1 row_mask:0xf bank_mask:0xf
	v_cndmask_b32_e64 v72, v60, v52, s[40:41]
	v_cndmask_b32_e64 v73, v61, v53, s[40:41]
	v_cndmask_b32_e64 v74, v62, v54, s[40:41]
	v_cndmask_b32_e64 v75, v63, v55, s[40:41]
	v_cndmask_b32_e64 v76, v56, v48, s[40:41]
	v_cndmask_b32_e64 v77, v57, v49, s[40:41]
	v_cndmask_b32_e64 v78, v58, v50, s[40:41]
	v_cndmask_b32_e64 v79, v59, v51, s[40:41]
	v_fmac_f32_dpp v220, v72, v124 row_ror:2 row_mask:0xf bank_mask:0xf
	v_fmac_f32_dpp v221, v73, v125 row_ror:2 row_mask:0xf bank_mask:0xf
	v_fmac_f32_dpp v222, v74, v126 row_ror:2 row_mask:0xf bank_mask:0xf
	v_fmac_f32_dpp v223, v75, v127 row_ror:2 row_mask:0xf bank_mask:0xf
	v_fmac_f32_dpp v224, v76, v120 row_ror:2 row_mask:0xf bank_mask:0xf
	v_fmac_f32_dpp v225, v77, v121 row_ror:2 row_mask:0xf bank_mask:0xf
	v_fmac_f32_dpp v226, v78, v122 row_ror:2 row_mask:0xf bank_mask:0xf
	v_fmac_f32_dpp v227, v79, v123 row_ror:2 row_mask:0xf bank_mask:0xf
	v_pk_mul_f32 v[190:191], v[220:221], s[100:101] op_sel_hi:[1,0]
	v_pk_mul_f32 v[250:251], v[222:223], s[100:101] op_sel_hi:[1,0]
	v_exp_f32_e32 v190, v190
	v_exp_f32_e32 v191, v191
	v_exp_f32_e32 v250, v250
	v_exp_f32_e32 v251, v251
	v_pk_mul_f32 v[220:221], v[220:221], v[224:225]
	v_pk_mul_f32 v[222:223], v[222:223], v[226:227]
	v_pk_add_f32 v[190:191], v[190:191], 1.0 op_sel_hi:[1,0]
	v_pk_add_f32 v[250:251], v[250:251], 1.0 op_sel_hi:[1,0]
	v_rcp_f32_e32 v190, v190
	v_rcp_f32_e32 v191, v191
	v_rcp_f32_e32 v250, v250
	v_rcp_f32_e32 v251, v251
	v_pk_mul_f32 v[220:221], v[220:221], v[190:191]
	v_pk_mul_f32 v[222:223], v[222:223], v[250:251]
	v_cvt_pk_bf16_f32 v196, v220, v221
	v_cvt_pk_bf16_f32 v197, v222, v223
	v_add_u32_e32 v243, 0x16000, v239
	global_store_dwordx4 v243, v[194:197], s[24:25]
	v_pk_fma_f32 v[220:221], v[108:109], v[44:45], v[100:101]
	v_pk_fma_f32 v[222:223], v[110:111], v[46:47], v[102:103]
	v_pk_fma_f32 v[224:225], v[104:105], v[40:41], v[96:97]
	v_pk_fma_f32 v[226:227], v[106:107], v[42:43], v[98:99]
	v_cndmask_b32_e64 v72, v44, v52, s[98:99]
	v_cndmask_b32_e64 v73, v45, v53, s[98:99]
	v_cndmask_b32_e64 v74, v46, v54, s[98:99]
	v_cndmask_b32_e64 v75, v47, v55, s[98:99]
	v_cndmask_b32_e64 v76, v40, v48, s[98:99]
	v_cndmask_b32_e64 v77, v41, v49, s[98:99]
	v_cndmask_b32_e64 v78, v42, v50, s[98:99]
	v_cndmask_b32_e64 v79, v43, v51, s[98:99]
	v_fmac_f32_dpp v220, v72, v116 row_ror:1 row_mask:0xf bank_mask:0xf
	v_fmac_f32_dpp v221, v73, v117 row_ror:1 row_mask:0xf bank_mask:0xf
	v_fmac_f32_dpp v222, v74, v118 row_ror:1 row_mask:0xf bank_mask:0xf
	v_fmac_f32_dpp v223, v75, v119 row_ror:1 row_mask:0xf bank_mask:0xf
	v_fmac_f32_dpp v224, v76, v112 row_ror:1 row_mask:0xf bank_mask:0xf
	v_fmac_f32_dpp v225, v77, v113 row_ror:1 row_mask:0xf bank_mask:0xf
	v_fmac_f32_dpp v226, v78, v114 row_ror:1 row_mask:0xf bank_mask:0xf
	v_fmac_f32_dpp v227, v79, v115 row_ror:1 row_mask:0xf bank_mask:0xf
	v_cndmask_b32_e64 v72, v52, v44, s[40:41]
	v_cndmask_b32_e64 v73, v53, v45, s[40:41]
	v_cndmask_b32_e64 v74, v54, v46, s[40:41]
	v_cndmask_b32_e64 v75, v55, v47, s[40:41]
	v_cndmask_b32_e64 v76, v48, v40, s[40:41]
	v_cndmask_b32_e64 v77, v49, v41, s[40:41]
	v_cndmask_b32_e64 v78, v50, v42, s[40:41]
	v_cndmask_b32_e64 v79, v51, v43, s[40:41]
	v_fmac_f32_dpp v220, v72, v124 row_ror:2 row_mask:0xf bank_mask:0xf
	v_fmac_f32_dpp v221, v73, v125 row_ror:2 row_mask:0xf bank_mask:0xf
	v_fmac_f32_dpp v222, v74, v126 row_ror:2 row_mask:0xf bank_mask:0xf
	v_fmac_f32_dpp v223, v75, v127 row_ror:2 row_mask:0xf bank_mask:0xf
	v_fmac_f32_dpp v224, v76, v120 row_ror:2 row_mask:0xf bank_mask:0xf
	v_fmac_f32_dpp v225, v77, v121 row_ror:2 row_mask:0xf bank_mask:0xf
	v_fmac_f32_dpp v226, v78, v122 row_ror:2 row_mask:0xf bank_mask:0xf
	v_fmac_f32_dpp v227, v79, v123 row_ror:2 row_mask:0xf bank_mask:0xf
	v_pk_mul_f32 v[190:191], v[220:221], s[100:101] op_sel_hi:[1,0]
	v_pk_mul_f32 v[250:251], v[222:223], s[100:101] op_sel_hi:[1,0]
	v_exp_f32_e32 v190, v190
	v_exp_f32_e32 v191, v191
	v_exp_f32_e32 v250, v250
	v_exp_f32_e32 v251, v251
	v_pk_mul_f32 v[220:221], v[220:221], v[224:225]
	v_pk_mul_f32 v[222:223], v[222:223], v[226:227]
	v_pk_add_f32 v[190:191], v[190:191], 1.0 op_sel_hi:[1,0]
	v_pk_add_f32 v[250:251], v[250:251], 1.0 op_sel_hi:[1,0]
	v_rcp_f32_e32 v190, v190
	v_rcp_f32_e32 v191, v191
	v_rcp_f32_e32 v250, v250
	v_rcp_f32_e32 v251, v251
; __device__ __forceinline__ unsigned cvt_pk_bf16(float lo, float hi) { unsigned r; asm volatile("v_cvt_pk_bf16_f32 %0, %1, %2" : "=v"(r) : "v"(lo), "v"(hi)); return r; }
; __device__ __forceinline__ float dpp_ror1(float x) { return __int_as_float(__builtin_amdgcn_update_dpp(0, __float_as_int(x), 0x121, 0xf, 0xf, false)); }
; __device__ __forceinline__ float dpp_ror2(float x) { return __int_as_float(__builtin_amdgcn_update_dpp(0, __float_as_int(x), 0x122, 0xf, 0xf, false)); }
; __device__ __forceinline__ float row_rstd(const float* slots, int row) {
;     const f32x4* s = (const f32x4*)(slots + (size_t)row * 16);
;     const f32x4 a = s[0], b = s[1], c = s[2], d = s[3];
;     __device__ __forceinline__ void operator()(const f32x4 (&acc)[2][2][4][2], const Unit& u, int wr, int wc, int fr, int fq) const {
;     ...
;                 for (int m = 0; m < 4; ++m) {
;                     f32x4 cur[2], h[2];
; #pragma unroll
;                     for (int bj = 0; bj < 2; ++bj) { cur[bj] = acc[ai][bj][m][n] * rs[ai][m]; f32x4 x1, x2;
; #pragma unroll
;                         for (int e = 0; e < 4; ++e) { const float c1 = dpp_ror1(cur[bj][e]), p1 = dpp_ror1(pg[bj][e]), c2 = dpp_ror2(cur[bj][e]), p2 = dpp_ror2(pg[bj][e]);
;                             x1[e] = fr >= 1 ? c1 : p1; x2[e] = fr >= 2 ? c2 : p2; }
;                         h[bj] = bb[bj] + w0[bj] * x2 + w1[bj] * x1 + w2[bj] * cur[bj]; }
;                     if (ai == 0 && wr == 0 && m == 0 && fr < 2) {
;                         *(f32x4*)(hc0 + (size_t)(u.pm * 2 + fr) * FF2 + gcol + 4 * n) = h[0]; *(f32x4*)(hc0 + (size_t)(u.pm * 2 + fr) * FF2 + FF + gcol + 4 * n) = h[1]; }
;                     f32x4 a;
; #pragma unroll
;                     for (int e = 0; e < 4; ++e) { const float g = h[0][e]; a[e] = g * __builtin_amdgcn_rcpf(1.0f + __builtin_amdgcn_exp2f(-1.4426950408889634f * g)) * h[1][e]; }
;                     const unsigned p0 = cvt_pk_bf16(a[0], a[1]), p1 = cvt_pk_bf16(a[2], a[3]);
;                     if (n == 0) { pk_lo[ai][m][0] = p0; pk_lo[ai][m][1] = p1; }
;                     else { u32x4 w; w.x = pk_lo[ai][m][0]; w.y = pk_lo[ai][m][1]; w.z = p0; w.w = p1;
;                         *(u32x4*)(act + (size_t)(u.pm * BM + ai * HALF + wr * 64 + m * 16 + fr) * FF + gcol) = w; }
	v_pk_mul_f32 v[220:221], v[220:221], v[190:191]
	v_pk_mul_f32 v[222:223], v[222:223], v[250:251]
	v_cvt_pk_bf16_f32 v200, v220, v221
	v_cvt_pk_bf16_f32 v201, v222, v223
	v_add_u32_e32 v243, 0x2c000, v239
	global_store_dwordx4 v243, v[198:201], s[24:25]
	v_pk_fma_f32 v[220:221], v[108:109], v[36:37], v[100:101]
	v_pk_fma_f32 v[222:223], v[110:111], v[38:39], v[102:103]
	v_pk_fma_f32 v[224:225], v[104:105], v[32:33], v[96:97]
	v_pk_fma_f32 v[226:227], v[106:107], v[34:35], v[98:99]
	v_cndmask_b32_e64 v72, v36, v44, s[98:99]
	v_cndmask_b32_e64 v73, v37, v45, s[98:99]
	v_cndmask_b32_e64 v74, v38, v46, s[98:99]
	v_cndmask_b32_e64 v75, v39, v47, s[98:99]
	v_cndmask_b32_e64 v76, v32, v40, s[98:99]
	v_cndmask_b32_e64 v77, v33, v41, s[98:99]
	v_cndmask_b32_e64 v78, v34, v42, s[98:99]
	v_cndmask_b32_e64 v79, v35, v43, s[98:99]
	v_fmac_f32_dpp v220, v72, v116 row_ror:1 row_mask:0xf bank_mask:0xf
	v_fmac_f32_dpp v221, v73, v117 row_ror:1 row_mask:0xf bank_mask:0xf
	v_fmac_f32_dpp v222, v74, v118 row_ror:1 row_mask:0xf bank_mask:0xf
	v_fmac_f32_dpp v223, v75, v119 row_ror:1 row_mask:0xf bank_mask:0xf
	v_fmac_f32_dpp v224, v76, v112 row_ror:1 row_mask:0xf bank_mask:0xf
	v_fmac_f32_dpp v225, v77, v113 row_ror:1 row_mask:0xf bank_mask:0xf
	v_fmac_f32_dpp v226, v78, v114 row_ror:1 row_mask:0xf bank_mask:0xf
	v_fmac_f32_dpp v227, v79, v115 row_ror:1 row_mask:0xf bank_mask:0xf
	v_cndmask_b32_e64 v72, v44, v36, s[40:41]
	v_cndmask_b32_e64 v73, v45, v37, s[40:41]
	v_cndmask_b32_e64 v74, v46, v38, s[40:41]
	v_cndmask_b32_e64 v75, v47, v39, s[40:41]
	v_cndmask_b32_e64 v76, v40, v32, s[40:41]
	v_cndmask_b32_e64 v77, v41, v33, s[40:41]
	v_cndmask_b32_e64 v78, v42, v34, s[40:41]
	v_cndmask_b32_e64 v79, v43, v35, s[40:41]
	v_fmac_f32_dpp v220, v72, v124 row_ror:2 row_mask:0xf bank_mask:0xf
	v_fmac_f32_dpp v221, v73, v125 row_ror:2 row_mask:0xf bank_mask:0xf
	v_fmac_f32_dpp v222, v74, v126 row_ror:2 row_mask:0xf bank_mask:0xf
	v_fmac_f32_dpp v223, v75, v127 row_ror:2 row_mask:0xf bank_mask:0xf
	v_fmac_f32_dpp v224, v76, v120 row_ror:2 row_mask:0xf bank_mask:0xf
	v_fmac_f32_dpp v225, v77, v121 row_ror:2 row_mask:0xf bank_mask:0xf
	v_fmac_f32_dpp v226, v78, v122 row_ror:2 row_mask:0xf bank_mask:0xf
	v_fmac_f32_dpp v227, v79, v123 row_ror:2 row_mask:0xf bank_mask:0xf
	v_pk_mul_f32 v[190:191], v[220:221], s[100:101] op_sel_hi:[1,0]
	v_pk_mul_f32 v[250:251], v[222:223], s[100:101] op_sel_hi:[1,0]
	v_exp_f32_e32 v190, v190
	v_exp_f32_e32 v191, v191
	v_exp_f32_e32 v250, v250
	v_exp_f32_e32 v251, v251
	v_pk_mul_f32 v[220:221], v[220:221], v[224:225]
	v_pk_mul_f32 v[222:223], v[222:223], v[226:227]
	v_pk_add_f32 v[190:191], v[190:191], 1.0 op_sel_hi:[1,0]
	v_pk_add_f32 v[250:251], v[250:251], 1.0 op_sel_hi:[1,0]
	v_rcp_f32_e32 v190, v190
	v_rcp_f32_e32 v191, v191
	v_rcp_f32_e32 v250, v250
	v_rcp_f32_e32 v251, v251
	v_pk_mul_f32 v[220:221], v[220:221], v[190:191]
	v_pk_mul_f32 v[222:223], v[222:223], v[250:251]
	v_cvt_pk_bf16_f32 v204, v220, v221
	v_cvt_pk_bf16_f32 v205, v222, v223
	v_add_u32_e32 v243, 0x42000, v239
	global_store_dwordx4 v243, v[202:205], s[24:25]
	s_and_b64 vcc, exec, s[46:47]
	s_cbranch_vccz .Lp7_nopf
	s_cmp_eq_u32 s10, s71
	s_cbranch_scc1 .Lp7_nopf
	s_lshl_b32 s78, s10, 8
	s_add_i32 s78, s78, s8
	s_mov_b32 s79, 1
	v_or_b32_e32 v229, s78, v209
	v_lshlrev_b32_e32 v229, 6, v229
	v_add_u32_e32 v231, 0x2000, v229
	global_load_dwordx4 v[60:63], v229, s[26:27]
	global_load_dwordx4 v[52:55], v229, s[26:27] offset:16
	global_load_dwordx4 v[44:47], v229, s[26:27] offset:32
	global_load_dwordx4 v[36:39], v229, s[26:27] offset:48
	global_load_dwordx4 v[56:59], v231, s[26:27]
	global_load_dwordx4 v[48:51], v231, s[26:27] offset:16
	global_load_dwordx4 v[40:43], v231, s[26:27] offset:32
	global_load_dwordx4 v[32:35], v231, s[26:27] offset:48
.Lp7_nopf:
	v_pk_fma_f32 v[220:221], v[108:109], v[28:29], v[100:101]
	v_pk_fma_f32 v[222:223], v[110:111], v[30:31], v[102:103]
	v_pk_fma_f32 v[224:225], v[104:105], v[24:25], v[96:97]
	v_pk_fma_f32 v[226:227], v[106:107], v[26:27], v[98:99]
	v_cndmask_b32_e64 v72, v28, v84, s[98:99]
	v_cndmask_b32_e64 v73, v29, v85, s[98:99]
	v_cndmask_b32_e64 v74, v30, v86, s[98:99]
	v_cndmask_b32_e64 v75, v31, v87, s[98:99]
	v_cndmask_b32_e64 v76, v24, v80, s[98:99]
	v_cndmask_b32_e64 v77, v25, v81, s[98:99]
	v_cndmask_b32_e64 v78, v26, v82, s[98:99]
	v_cndmask_b32_e64 v79, v27, v83, s[98:99]
	v_fmac_f32_dpp v220, v72, v116 row_ror:1 row_mask:0xf bank_mask:0xf
	v_fmac_f32_dpp v221, v73, v117 row_ror:1 row_mask:0xf bank_mask:0xf
	v_fmac_f32_dpp v222, v74, v118 row_ror:1 row_mask:0xf bank_mask:0xf
	v_fmac_f32_dpp v223, v75, v119 row_ror:1 row_mask:0xf bank_mask:0xf
	v_fmac_f32_dpp v224, v76, v112 row_ror:1 row_mask:0xf bank_mask:0xf
	v_fmac_f32_dpp v225, v77, v113 row_ror:1 row_mask:0xf bank_mask:0xf
	v_fmac_f32_dpp v226, v78, v114 row_ror:1 row_mask:0xf bank_mask:0xf
	v_fmac_f32_dpp v227, v79, v115 row_ror:1 row_mask:0xf bank_mask:0xf
	v_cndmask_b32_e64 v72, v84, v28, s[40:41]
	v_cndmask_b32_e64 v73, v85, v29, s[40:41]
	v_cndmask_b32_e64 v74, v86, v30, s[40:41]
	v_cndmask_b32_e64 v75, v87, v31, s[40:41]
	v_cndmask_b32_e64 v76, v80, v24, s[40:41]
	v_cndmask_b32_e64 v77, v81, v25, s[40:41]
	v_cndmask_b32_e64 v78, v82, v26, s[40:41]
	v_cndmask_b32_e64 v79, v83, v27, s[40:41]
	v_fmac_f32_dpp v220, v72, v124 row_ror:2 row_mask:0xf bank_mask:0xf
	v_fmac_f32_dpp v221, v73, v125 row_ror:2 row_mask:0xf bank_mask:0xf
	v_fmac_f32_dpp v222, v74, v126 row_ror:2 row_mask:0xf bank_mask:0xf
	v_fmac_f32_dpp v223, v75, v127 row_ror:2 row_mask:0xf bank_mask:0xf
	v_fmac_f32_dpp v224, v76, v120 row_ror:2 row_mask:0xf bank_mask:0xf
; __device__ __forceinline__ unsigned cvt_pk_bf16(float lo, float hi) { unsigned r; asm volatile("v_cvt_pk_bf16_f32 %0, %1, %2" : "=v"(r) : "v"(lo), "v"(hi)); return r; }
; __device__ __forceinline__ float dpp_ror1(float x) { return __int_as_float(__builtin_amdgcn_update_dpp(0, __float_as_int(x), 0x121, 0xf, 0xf, false)); }
; __device__ __forceinline__ float dpp_ror2(float x) { return __int_as_float(__builtin_amdgcn_update_dpp(0, __float_as_int(x), 0x122, 0xf, 0xf, false)); }
;     __device__ __forceinline__ void operator()(const f32x4 (&acc)[2][2][4][2], const Unit& u, int wr, int wc, int fr, int fq) const {
;     ...
;                 for (int m = 0; m < 4; ++m) {
;                     f32x4 cur[2], h[2];
; #pragma unroll
;                     for (int bj = 0; bj < 2; ++bj) { cur[bj] = acc[ai][bj][m][n] * rs[ai][m]; f32x4 x1, x2;
; #pragma unroll
;                         for (int e = 0; e < 4; ++e) { const float c1 = dpp_ror1(cur[bj][e]), p1 = dpp_ror1(pg[bj][e]), c2 = dpp_ror2(cur[bj][e]), p2 = dpp_ror2(pg[bj][e]);
;                             x1[e] = fr >= 1 ? c1 : p1; x2[e] = fr >= 2 ? c2 : p2; }
;                         h[bj] = bb[bj] + w0[bj] * x2 + w1[bj] * x1 + w2[bj] * cur[bj]; }
;                     if (ai == 0 && wr == 0 && m == 0 && fr < 2) {
;                         *(f32x4*)(hc0 + (size_t)(u.pm * 2 + fr) * FF2 + gcol + 4 * n) = h[0]; *(f32x4*)(hc0 + (size_t)(u.pm * 2 + fr) * FF2 + FF + gcol + 4 * n) = h[1]; }
;                     f32x4 a;
; #pragma unroll
;                     for (int e = 0; e < 4; ++e) { const float g = h[0][e]; a[e] = g * __builtin_amdgcn_rcpf(1.0f + __builtin_amdgcn_exp2f(-1.4426950408889634f * g)) * h[1][e]; }
;                     const unsigned p0 = cvt_pk_bf16(a[0], a[1]), p1 = cvt_pk_bf16(a[2], a[3]);
;                     if (n == 0) { pk_lo[ai][m][0] = p0; pk_lo[ai][m][1] = p1; }
;                     else { u32x4 w; w.x = pk_lo[ai][m][0]; w.y = pk_lo[ai][m][1]; w.z = p0; w.w = p1;
;                         *(u32x4*)(act + (size_t)(u.pm * BM + ai * HALF + wr * 64 + m * 16 + fr) * FF + gcol) = w; }
	v_fmac_f32_dpp v225, v77, v121 row_ror:2 row_mask:0xf bank_mask:0xf
	v_fmac_f32_dpp v226, v78, v122 row_ror:2 row_mask:0xf bank_mask:0xf
	v_fmac_f32_dpp v227, v79, v123 row_ror:2 row_mask:0xf bank_mask:0xf
	v_pk_mul_f32 v[190:191], v[220:221], s[100:101] op_sel_hi:[1,0]
	v_pk_mul_f32 v[250:251], v[222:223], s[100:101] op_sel_hi:[1,0]
	v_exp_f32_e32 v190, v190
	v_exp_f32_e32 v191, v191
	v_exp_f32_e32 v250, v250
	v_exp_f32_e32 v251, v251
	v_pk_mul_f32 v[220:221], v[220:221], v[224:225]
	v_pk_mul_f32 v[222:223], v[222:223], v[226:227]
	v_pk_add_f32 v[190:191], v[190:191], 1.0 op_sel_hi:[1,0]
	v_pk_add_f32 v[250:251], v[250:251], 1.0 op_sel_hi:[1,0]
	v_rcp_f32_e32 v190, v190
	v_rcp_f32_e32 v191, v191
	v_rcp_f32_e32 v250, v250
	v_rcp_f32_e32 v251, v251
	v_pk_mul_f32 v[220:221], v[220:221], v[190:191]
	v_pk_mul_f32 v[222:223], v[222:223], v[250:251]
	v_cvt_pk_bf16_f32 v162, v220, v221
	v_cvt_pk_bf16_f32 v163, v222, v223
	v_add_u32_e32 v243, 0xb0000, v239
	global_store_dwordx4 v243, v[160:163], s[24:25]
	v_pk_fma_f32 v[220:221], v[108:109], v[20:21], v[100:101]
	v_pk_fma_f32 v[222:223], v[110:111], v[22:23], v[102:103]
	v_pk_fma_f32 v[224:225], v[104:105], v[16:17], v[96:97]
	v_pk_fma_f32 v[226:227], v[106:107], v[18:19], v[98:99]
	v_cndmask_b32_e64 v72, v20, v28, s[98:99]
	v_cndmask_b32_e64 v73, v21, v29, s[98:99]
	v_cndmask_b32_e64 v74, v22, v30, s[98:99]
	v_cndmask_b32_e64 v75, v23, v31, s[98:99]
	v_cndmask_b32_e64 v76, v16, v24, s[98:99]
	v_cndmask_b32_e64 v77, v17, v25, s[98:99]
	v_cndmask_b32_e64 v78, v18, v26, s[98:99]
	v_cndmask_b32_e64 v79, v19, v27, s[98:99]
	v_fmac_f32_dpp v220, v72, v116 row_ror:1 row_mask:0xf bank_mask:0xf
	v_fmac_f32_dpp v221, v73, v117 row_ror:1 row_mask:0xf bank_mask:0xf
	v_fmac_f32_dpp v222, v74, v118 row_ror:1 row_mask:0xf bank_mask:0xf
	v_fmac_f32_dpp v223, v75, v119 row_ror:1 row_mask:0xf bank_mask:0xf
	v_fmac_f32_dpp v224, v76, v112 row_ror:1 row_mask:0xf bank_mask:0xf
	v_fmac_f32_dpp v225, v77, v113 row_ror:1 row_mask:0xf bank_mask:0xf
	v_fmac_f32_dpp v226, v78, v114 row_ror:1 row_mask:0xf bank_mask:0xf
	v_fmac_f32_dpp v227, v79, v115 row_ror:1 row_mask:0xf bank_mask:0xf
	v_cndmask_b32_e64 v72, v28, v20, s[40:41]
	v_cndmask_b32_e64 v73, v29, v21, s[40:41]
	v_cndmask_b32_e64 v74, v30, v22, s[40:41]
	v_cndmask_b32_e64 v75, v31, v23, s[40:41]
	v_cndmask_b32_e64 v76, v24, v16, s[40:41]
	v_cndmask_b32_e64 v77, v25, v17, s[40:41]
	v_cndmask_b32_e64 v78, v26, v18, s[40:41]
	v_cndmask_b32_e64 v79, v27, v19, s[40:41]
	v_fmac_f32_dpp v220, v72, v124 row_ror:2 row_mask:0xf bank_mask:0xf
	v_fmac_f32_dpp v221, v73, v125 row_ror:2 row_mask:0xf bank_mask:0xf
	v_fmac_f32_dpp v222, v74, v126 row_ror:2 row_mask:0xf bank_mask:0xf
	v_fmac_f32_dpp v223, v75, v127 row_ror:2 row_mask:0xf bank_mask:0xf
	v_fmac_f32_dpp v224, v76, v120 row_ror:2 row_mask:0xf bank_mask:0xf
	v_fmac_f32_dpp v225, v77, v121 row_ror:2 row_mask:0xf bank_mask:0xf
	v_fmac_f32_dpp v226, v78, v122 row_ror:2 row_mask:0xf bank_mask:0xf
	v_fmac_f32_dpp v227, v79, v123 row_ror:2 row_mask:0xf bank_mask:0xf
	v_pk_mul_f32 v[190:191], v[220:221], s[100:101] op_sel_hi:[1,0]
	v_pk_mul_f32 v[250:251], v[222:223], s[100:101] op_sel_hi:[1,0]
	v_exp_f32_e32 v190, v190
	v_exp_f32_e32 v191, v191
	v_exp_f32_e32 v250, v250
	v_exp_f32_e32 v251, v251
	v_pk_mul_f32 v[220:221], v[220:221], v[224:225]
	v_pk_mul_f32 v[222:223], v[222:223], v[226:227]
	v_pk_add_f32 v[190:191], v[190:191], 1.0 op_sel_hi:[1,0]
	v_pk_add_f32 v[250:251], v[250:251], 1.0 op_sel_hi:[1,0]
	v_rcp_f32_e32 v190, v190
	v_rcp_f32_e32 v191, v191
	v_rcp_f32_e32 v250, v250
	v_rcp_f32_e32 v251, v251
	v_pk_mul_f32 v[220:221], v[220:221], v[190:191]
	v_pk_mul_f32 v[222:223], v[222:223], v[250:251]
	v_cvt_pk_bf16_f32 v166, v220, v221
	v_cvt_pk_bf16_f32 v167, v222, v223
	v_add_u32_e32 v243, 0xc6000, v239
	global_store_dwordx4 v243, v[164:167], s[24:25]
	v_pk_fma_f32 v[220:221], v[108:109], v[12:13], v[100:101]
	v_pk_fma_f32 v[222:223], v[110:111], v[14:15], v[102:103]
	v_pk_fma_f32 v[224:225], v[104:105], v[8:9], v[96:97]
	v_pk_fma_f32 v[226:227], v[106:107], v[10:11], v[98:99]
	v_cndmask_b32_e64 v72, v12, v20, s[98:99]
	v_cndmask_b32_e64 v73, v13, v21, s[98:99]
	v_cndmask_b32_e64 v74, v14, v22, s[98:99]
	v_cndmask_b32_e64 v75, v15, v23, s[98:99]
	v_cndmask_b32_e64 v76, v8, v16, s[98:99]
	v_cndmask_b32_e64 v77, v9, v17, s[98:99]
	v_cndmask_b32_e64 v78, v10, v18, s[98:99]
	v_cndmask_b32_e64 v79, v11, v19, s[98:99]
	v_fmac_f32_dpp v220, v72, v116 row_ror:1 row_mask:0xf bank_mask:0xf
	v_fmac_f32_dpp v221, v73, v117 row_ror:1 row_mask:0xf bank_mask:0xf
	v_fmac_f32_dpp v222, v74, v118 row_ror:1 row_mask:0xf bank_mask:0xf
	v_fmac_f32_dpp v223, v75, v119 row_ror:1 row_mask:0xf bank_mask:0xf
	v_fmac_f32_dpp v224, v76, v112 row_ror:1 row_mask:0xf bank_mask:0xf
	v_fmac_f32_dpp v225, v77, v113 row_ror:1 row_mask:0xf bank_mask:0xf
	v_fmac_f32_dpp v226, v78, v114 row_ror:1 row_mask:0xf bank_mask:0xf
	v_fmac_f32_dpp v227, v79, v115 row_ror:1 row_mask:0xf bank_mask:0xf
	v_cndmask_b32_e64 v72, v20, v12, s[40:41]
	v_cndmask_b32_e64 v73, v21, v13, s[40:41]
	v_cndmask_b32_e64 v74, v22, v14, s[40:41]
	v_cndmask_b32_e64 v75, v23, v15, s[40:41]
	v_cndmask_b32_e64 v76, v16, v8, s[40:41]
	v_cndmask_b32_e64 v77, v17, v9, s[40:41]
	v_cndmask_b32_e64 v78, v18, v10, s[40:41]
	v_cndmask_b32_e64 v79, v19, v11, s[40:41]
	v_fmac_f32_dpp v220, v72, v124 row_ror:2 row_mask:0xf bank_mask:0xf
; __device__ __forceinline__ float row_rstd(const float* slots, int row) {
;     const f32x4* s = (const f32x4*)(slots + (size_t)row * 16);
;     const f32x4 a = s[0], b = s[1], c = s[2], d = s[3];
;     const f32x4 t = (a + b) + (c + d);
;     const float ss = (t[0] + t[1]) + (t[2] + t[3]);
;     return __builtin_amdgcn_rsqf(ss * (1.0f / 1024.0f) + 1e-6f);
; }
; __device__ __forceinline__ void load_rs(const float* slots, int rowbase, int fr, int fq, float scale, float (&rs)[2][4]) {
;     float loc[2];
; #pragma unroll
;     for (int ai = 0; ai < 2; ++ai) loc[ai] = scale * row_rstd(slots, rowbase + ai * HALF + fq * 16 + fr);
; #pragma unroll
;     for (int ai = 0; ai < 2; ++ai)
; #pragma unroll
;         for (int m = 0; m < 4; ++m) rs[ai][m] = __shfl(loc[ai], m * 16 + fr);
;     __device__ __forceinline__ void operator()(const f32x4 (&acc)[2][2][4][2], const Unit& u, int wr, int wc, int fr, int fq) const {
;     ...
;                 for (int m = 0; m < 4; ++m) {
;                     f32x4 cur[2], h[2];
; #pragma unroll
;                     for (int bj = 0; bj < 2; ++bj) { cur[bj] = acc[ai][bj][m][n] * rs[ai][m]; f32x4 x1, x2;
; #pragma unroll
;                         for (int e = 0; e < 4; ++e) { const float c1 = dpp_ror1(cur[bj][e]), p1 = dpp_ror1(pg[bj][e]), c2 = dpp_ror2(cur[bj][e]), p2 = dpp_ror2(pg[bj][e]);
;                             x1[e] = fr >= 1 ? c1 : p1; x2[e] = fr >= 2 ? c2 : p2; }
;                         h[bj] = bb[bj] + w0[bj] * x2 + w1[bj] * x1 + w2[bj] * cur[bj]; }
;                     if (ai == 0 && wr == 0 && m == 0 && fr < 2) {
;                         *(f32x4*)(hc0 + (size_t)(u.pm * 2 + fr) * FF2 + gcol + 4 * n) = h[0]; *(f32x4*)(hc0 + (size_t)(u.pm * 2 + fr) * FF2 + FF + gcol + 4 * n) = h[1]; }
;                     f32x4 a;
; #pragma unroll
;                     for (int e = 0; e < 4; ++e) { const float g = h[0][e]; a[e] = g * __builtin_amdgcn_rcpf(1.0f + __builtin_amdgcn_exp2f(-1.4426950408889634f * g)) * h[1][e]; }
;                     const unsigned p0 = cvt_pk_bf16(a[0], a[1]), p1 = cvt_pk_bf16(a[2], a[3]);
;                     if (n == 0) { pk_lo[ai][m][0] = p0; pk_lo[ai][m][1] = p1; }
;                     else { u32x4 w; w.x = pk_lo[ai][m][0]; w.y = pk_lo[ai][m][1]; w.z = p0; w.w = p1;
;                         *(u32x4*)(act + (size_t)(u.pm * BM + ai * HALF + wr * 64 + m * 16 + fr) * FF + gcol) = w; }
	v_fmac_f32_dpp v221, v73, v125 row_ror:2 row_mask:0xf bank_mask:0xf
	v_fmac_f32_dpp v222, v74, v126 row_ror:2 row_mask:0xf bank_mask:0xf
	v_fmac_f32_dpp v223, v75, v127 row_ror:2 row_mask:0xf bank_mask:0xf
	v_fmac_f32_dpp v224, v76, v120 row_ror:2 row_mask:0xf bank_mask:0xf
	v_fmac_f32_dpp v225, v77, v121 row_ror:2 row_mask:0xf bank_mask:0xf
	v_fmac_f32_dpp v226, v78, v122 row_ror:2 row_mask:0xf bank_mask:0xf
	v_fmac_f32_dpp v227, v79, v123 row_ror:2 row_mask:0xf bank_mask:0xf
	v_pk_mul_f32 v[190:191], v[220:221], s[100:101] op_sel_hi:[1,0]
	v_pk_mul_f32 v[250:251], v[222:223], s[100:101] op_sel_hi:[1,0]
	v_exp_f32_e32 v190, v190
	v_exp_f32_e32 v191, v191
	v_exp_f32_e32 v250, v250
	v_exp_f32_e32 v251, v251
	v_pk_mul_f32 v[220:221], v[220:221], v[224:225]
	v_pk_mul_f32 v[222:223], v[222:223], v[226:227]
	v_pk_add_f32 v[190:191], v[190:191], 1.0 op_sel_hi:[1,0]
	v_pk_add_f32 v[250:251], v[250:251], 1.0 op_sel_hi:[1,0]
	v_rcp_f32_e32 v190, v190
	v_rcp_f32_e32 v191, v191
	v_rcp_f32_e32 v250, v250
	v_rcp_f32_e32 v251, v251
	v_pk_mul_f32 v[220:221], v[220:221], v[190:191]
	v_pk_mul_f32 v[222:223], v[222:223], v[250:251]
	v_cvt_pk_bf16_f32 v180, v220, v221
	v_cvt_pk_bf16_f32 v181, v222, v223
	v_add_u32_e32 v243, 0xdc000, v239
	global_store_dwordx4 v243, v[178:181], s[24:25]
	v_pk_fma_f32 v[220:221], v[108:109], v[4:5], v[100:101]
	v_pk_fma_f32 v[222:223], v[110:111], v[6:7], v[102:103]
	v_pk_fma_f32 v[224:225], v[104:105], v[0:1], v[96:97]
	v_pk_fma_f32 v[226:227], v[106:107], v[2:3], v[98:99]
	v_cndmask_b32_e64 v72, v4, v12, s[98:99]
	v_cndmask_b32_e64 v73, v5, v13, s[98:99]
	v_cndmask_b32_e64 v74, v6, v14, s[98:99]
	v_cndmask_b32_e64 v75, v7, v15, s[98:99]
	v_cndmask_b32_e64 v76, v0, v8, s[98:99]
	v_cndmask_b32_e64 v77, v1, v9, s[98:99]
	v_cndmask_b32_e64 v78, v2, v10, s[98:99]
	v_cndmask_b32_e64 v79, v3, v11, s[98:99]
	v_fmac_f32_dpp v220, v72, v116 row_ror:1 row_mask:0xf bank_mask:0xf
	v_fmac_f32_dpp v221, v73, v117 row_ror:1 row_mask:0xf bank_mask:0xf
	v_fmac_f32_dpp v222, v74, v118 row_ror:1 row_mask:0xf bank_mask:0xf
	v_fmac_f32_dpp v223, v75, v119 row_ror:1 row_mask:0xf bank_mask:0xf
	v_fmac_f32_dpp v224, v76, v112 row_ror:1 row_mask:0xf bank_mask:0xf
	v_fmac_f32_dpp v225, v77, v113 row_ror:1 row_mask:0xf bank_mask:0xf
	v_fmac_f32_dpp v226, v78, v114 row_ror:1 row_mask:0xf bank_mask:0xf
	v_fmac_f32_dpp v227, v79, v115 row_ror:1 row_mask:0xf bank_mask:0xf
	v_cndmask_b32_e64 v72, v12, v4, s[40:41]
	v_cndmask_b32_e64 v73, v13, v5, s[40:41]
	v_cndmask_b32_e64 v74, v14, v6, s[40:41]
	v_cndmask_b32_e64 v75, v15, v7, s[40:41]
	v_cndmask_b32_e64 v76, v8, v0, s[40:41]
	v_cndmask_b32_e64 v77, v9, v1, s[40:41]
	v_cndmask_b32_e64 v78, v10, v2, s[40:41]
	v_cndmask_b32_e64 v79, v11, v3, s[40:41]
	v_fmac_f32_dpp v220, v72, v124 row_ror:2 row_mask:0xf bank_mask:0xf
	v_fmac_f32_dpp v221, v73, v125 row_ror:2 row_mask:0xf bank_mask:0xf
	v_fmac_f32_dpp v222, v74, v126 row_ror:2 row_mask:0xf bank_mask:0xf
	v_fmac_f32_dpp v223, v75, v127 row_ror:2 row_mask:0xf bank_mask:0xf
	v_fmac_f32_dpp v224, v76, v120 row_ror:2 row_mask:0xf bank_mask:0xf
	v_fmac_f32_dpp v225, v77, v121 row_ror:2 row_mask:0xf bank_mask:0xf
	v_fmac_f32_dpp v226, v78, v122 row_ror:2 row_mask:0xf bank_mask:0xf
	v_fmac_f32_dpp v227, v79, v123 row_ror:2 row_mask:0xf bank_mask:0xf
	v_pk_mul_f32 v[190:191], v[220:221], s[100:101] op_sel_hi:[1,0]
	v_pk_mul_f32 v[250:251], v[222:223], s[100:101] op_sel_hi:[1,0]
	v_exp_f32_e32 v190, v190
	v_exp_f32_e32 v191, v191
	v_exp_f32_e32 v250, v250
	v_exp_f32_e32 v251, v251
	v_pk_mul_f32 v[220:221], v[220:221], v[224:225]
	v_pk_mul_f32 v[222:223], v[222:223], v[226:227]
	v_pk_add_f32 v[190:191], v[190:191], 1.0 op_sel_hi:[1,0]
	v_pk_add_f32 v[250:251], v[250:251], 1.0 op_sel_hi:[1,0]
	v_rcp_f32_e32 v190, v190
	v_rcp_f32_e32 v191, v191
	v_rcp_f32_e32 v250, v250
	v_rcp_f32_e32 v251, v251
	v_pk_mul_f32 v[220:221], v[220:221], v[190:191]
	v_pk_mul_f32 v[222:223], v[222:223], v[250:251]
	v_cvt_pk_bf16_f32 v184, v220, v221
	v_cvt_pk_bf16_f32 v185, v222, v223
	v_add_u32_e32 v243, 0xf2000, v239
	global_store_dwordx4 v243, v[182:185], s[24:25]
	s_cmp_eq_u32 s79, 0
	s_cbranch_scc1 .Lp7_nored
	s_waitcnt vmcnt(4)
	v_pk_add_f32 v[62:63], v[62:63], v[54:55]
	v_pk_add_f32 v[58:59], v[58:59], v[50:51]
	v_pk_add_f32 v[60:61], v[60:61], v[52:53]
	v_pk_add_f32 v[56:57], v[56:57], v[48:49]
	v_pk_add_f32 v[52:53], v[46:47], v[38:39]
	v_pk_add_f32 v[48:49], v[42:43], v[34:35]
	v_pk_add_f32 v[54:55], v[44:45], v[36:37]
	v_pk_add_f32 v[50:51], v[40:41], v[32:33]
	v_pk_add_f32 v[62:63], v[62:63], v[52:53]
	v_pk_add_f32 v[58:59], v[58:59], v[48:49]
	v_pk_add_f32 v[60:61], v[60:61], v[54:55]
	v_pk_add_f32 v[56:57], v[56:57], v[50:51]
	v_add_f32_e32 v60, v60, v61
	v_add_f32_e32 v56, v56, v57
	v_add_f32_e32 v61, v62, v63
	v_add_f32_e32 v57, v58, v59
	v_add_f32_e32 v60, v60, v61
	v_add_f32_e32 v56, v56, v57
	v_fmamk_f32 v60, v60, 0x3a800000, v244
	v_fmamk_f32 v56, v56, 0x3a800000, v244
	v_rsq_f32_e32 v60, v60
	v_rsq_f32_e32 v56, v56
	ds_bpermute_b32 v228, v237, v60
	ds_bpermute_b32 v230, v237, v60 offset:64
	ds_bpermute_b32 v232, v237, v60 offset:128
	ds_bpermute_b32 v234, v237, v60 offset:192
	ds_bpermute_b32 v236, v237, v56
	ds_bpermute_b32 v238, v237, v56 offset:64
	ds_bpermute_b32 v240, v237, v56 offset:128
	ds_bpermute_b32 v248, v237, v56 offset:192
	s_mov_b32 s101, s10
